# GEMM k-loops: an extra s_setprio 0 / s_setprio 1 flip after the 8th MFMA of every 16-MFMA cluster (more priority windows for the partner group's LDS reads)
# speedup vs baseline: 1.0019x; 1.0015x over previous
.LBB0_145:
	s_add_u32 s27, s50, 0x100
	s_addc_u32 s56, s51, 0
	s_mov_b32 s57, -2
	s_waitcnt lgkmcnt(0)
	ds_read_b128 v[128:131], v188
	ds_read_b128 v[132:135], v188 offset:1024
	ds_read_b128 v[136:139], v188 offset:2048
	ds_read_b128 v[140:143], v188 offset:3072
	ds_read_b128 v[144:147], v189
	ds_read_b128 v[148:151], v189 offset:1024
	ds_read_b128 v[176:179], v189 offset:2048
	ds_read_b128 v[180:183], v189 offset:3072
	s_add_u32 s50, s48, 0x100
	s_addc_u32 s51, s49, 0
	s_cmp_eq_u32 s57, 28
	s_cselect_b32 s55, s21, s51
	s_cselect_b32 s54, s20, s50
	s_cselect_b32 s53, s23, s56
	s_cselect_b32 s52, s22, s27
	v_lshl_add_u64 v[184:185], s[48:49], 0, v[170:171]
	s_add_i32 m0, s60, 0xc000
	ds_read_b128 v[194:197], v190
	ds_read_b128 v[198:201], v190 offset:1024
	ds_read_b128 v[202:205], v190 offset:2048
	ds_read_b128 v[206:209], v190 offset:3072
	ds_read_b128 v[210:213], v190 offset:4096
	ds_read_b128 v[214:217], v190 offset:5120
	ds_read_b128 v[218:221], v190 offset:6144
	ds_read_b128 v[222:225], v190 offset:7168
	global_load_lds_dwordx4 v[184:185], off
	v_lshl_add_u64 v[184:185], s[48:49], 0, v[172:173]
	s_add_i32 m0, s60, 0xe000
	s_nop 0
	global_load_lds_dwordx4 v[184:185], off
	s_waitcnt vmcnt(8) lgkmcnt(0)
	s_setprio 1
	s_barrier
	v_mfma_f32_16x16x32_bf16 v[120:123], v[128:131], v[194:197], 0
	v_mfma_f32_16x16x32_bf16 v[124:127], v[136:139], v[194:197], 0
	v_mfma_f32_16x16x32_bf16 v[108:111], v[128:131], v[202:205], 0
	v_mfma_f32_16x16x32_bf16 v[104:107], v[136:139], v[202:205], 0
	v_mfma_f32_16x16x32_bf16 v[92:95], v[128:131], v[210:213], 0
	v_mfma_f32_16x16x32_bf16 v[88:91], v[136:139], v[210:213], 0
	v_mfma_f32_16x16x32_bf16 v[76:79], v[128:131], v[218:221], 0
	v_mfma_f32_16x16x32_bf16 v[72:75], v[136:139], v[218:221], 0
	s_setprio 0
	s_setprio 1
	v_mfma_f32_16x16x32_bf16 v[120:123], v[132:135], v[198:201], v[120:123]
	v_mfma_f32_16x16x32_bf16 v[124:127], v[140:143], v[198:201], v[124:127]
	v_mfma_f32_16x16x32_bf16 v[108:111], v[132:135], v[206:209], v[108:111]
	v_mfma_f32_16x16x32_bf16 v[104:107], v[140:143], v[206:209], v[104:107]
	v_mfma_f32_16x16x32_bf16 v[92:95], v[132:135], v[214:217], v[92:95]
	v_mfma_f32_16x16x32_bf16 v[88:91], v[140:143], v[214:217], v[88:91]
	v_mfma_f32_16x16x32_bf16 v[76:79], v[132:135], v[222:225], v[76:79]
	v_mfma_f32_16x16x32_bf16 v[72:75], v[140:143], v[222:225], v[72:75]
	s_setprio 0
	s_setprio 1
	v_mfma_f32_16x16x32_bf16 v[112:115], v[144:147], v[194:197], 0
	v_mfma_f32_16x16x32_bf16 v[116:119], v[176:179], v[194:197], 0
	v_mfma_f32_16x16x32_bf16 v[100:103], v[144:147], v[202:205], 0
	v_mfma_f32_16x16x32_bf16 v[96:99], v[176:179], v[202:205], 0
	v_mfma_f32_16x16x32_bf16 v[84:87], v[144:147], v[210:213], 0
	v_mfma_f32_16x16x32_bf16 v[80:83], v[176:179], v[210:213], 0
	v_mfma_f32_16x16x32_bf16 v[68:71], v[144:147], v[218:221], 0
	v_mfma_f32_16x16x32_bf16 v[64:67], v[176:179], v[218:221], 0
	s_setprio 0
	s_setprio 1
	v_mfma_f32_16x16x32_bf16 v[112:115], v[148:151], v[198:201], v[112:115]
	v_mfma_f32_16x16x32_bf16 v[116:119], v[180:183], v[198:201], v[116:119]
	v_mfma_f32_16x16x32_bf16 v[100:103], v[148:151], v[206:209], v[100:103]
	v_mfma_f32_16x16x32_bf16 v[96:99], v[180:183], v[206:209], v[96:99]
	v_mfma_f32_16x16x32_bf16 v[84:87], v[148:151], v[214:217], v[84:87]
	v_mfma_f32_16x16x32_bf16 v[80:83], v[180:183], v[214:217], v[80:83]
	v_mfma_f32_16x16x32_bf16 v[68:71], v[148:151], v[222:225], v[68:71]
	v_mfma_f32_16x16x32_bf16 v[64:67], v[180:183], v[222:225], v[64:67]
	s_barrier
	s_setprio 0
	s_add_i32 s48, s71, s3
	v_lshl_add_u64 v[184:185], s[52:53], 0, v[154:155]
	s_mov_b32 m0, s48
	ds_read_b128 v[194:197], v190 offset:16384
	ds_read_b128 v[198:201], v190 offset:17408
	ds_read_b128 v[202:205], v190 offset:18432
	ds_read_b128 v[206:209], v190 offset:19456
	ds_read_b128 v[210:213], v190 offset:20480
	ds_read_b128 v[214:217], v190 offset:21504
	ds_read_b128 v[218:221], v190 offset:22528
	ds_read_b128 v[222:225], v190 offset:23552
	global_load_lds_dwordx4 v[184:185], off
	s_add_i32 m0, s48, 0x2000
	s_add_u32 s48, s52, 0x80000
	v_lshl_add_u64 v[226:227], s[52:53], 0, v[158:159]
	s_addc_u32 s49, s53, 0
	s_add_i32 s58, s72, s3
	global_load_lds_dwordx4 v[226:227], off
	v_lshl_add_u64 v[228:229], s[48:49], 0, v[154:155]
	s_mov_b32 m0, s58
	v_lshl_add_u64 v[230:231], s[54:55], 0, v[156:157]
	global_load_lds_dwordx4 v[228:229], off
	v_lshl_add_u64 v[228:229], s[48:49], 0, v[158:159]
	s_add_i32 m0, s58, 0x2000
	s_nop 0
	global_load_lds_dwordx4 v[228:229], off
	v_lshl_add_u64 v[228:229], s[54:55], 0, v[152:153]
	s_mov_b32 m0, s60
	s_nop 0
	global_load_lds_dwordx4 v[228:229], off
	s_mov_b32 m0, s61
	s_nop 0
	global_load_lds_dwordx4 v[230:231], off
	s_waitcnt vmcnt(8) lgkmcnt(0)
	s_setprio 1
	s_barrier
	v_mfma_f32_16x16x32_bf16 v[60:63], v[128:131], v[194:197], 0
	v_mfma_f32_16x16x32_bf16 v[56:59], v[136:139], v[194:197], 0
	v_mfma_f32_16x16x32_bf16 v[44:47], v[128:131], v[202:205], 0
	v_mfma_f32_16x16x32_bf16 v[40:43], v[136:139], v[202:205], 0
	v_mfma_f32_16x16x32_bf16 v[28:31], v[128:131], v[210:213], 0
	v_mfma_f32_16x16x32_bf16 v[24:27], v[136:139], v[210:213], 0
	v_mfma_f32_16x16x32_bf16 v[12:15], v[128:131], v[218:221], 0
	v_mfma_f32_16x16x32_bf16 v[8:11], v[136:139], v[218:221], 0
	s_setprio 0
	s_setprio 1
	v_mfma_f32_16x16x32_bf16 v[60:63], v[132:135], v[198:201], v[60:63]
	v_mfma_f32_16x16x32_bf16 v[56:59], v[140:143], v[198:201], v[56:59]
	v_mfma_f32_16x16x32_bf16 v[44:47], v[132:135], v[206:209], v[44:47]
	v_mfma_f32_16x16x32_bf16 v[40:43], v[140:143], v[206:209], v[40:43]
	v_mfma_f32_16x16x32_bf16 v[28:31], v[132:135], v[214:217], v[28:31]
	v_mfma_f32_16x16x32_bf16 v[24:27], v[140:143], v[214:217], v[24:27]
	v_mfma_f32_16x16x32_bf16 v[12:15], v[132:135], v[222:225], v[12:15]
	v_mfma_f32_16x16x32_bf16 v[8:11], v[140:143], v[222:225], v[8:11]
	s_setprio 0
	s_setprio 1
	v_mfma_f32_16x16x32_bf16 v[52:55], v[144:147], v[194:197], 0
	v_mfma_f32_16x16x32_bf16 v[48:51], v[176:179], v[194:197], 0
	v_mfma_f32_16x16x32_bf16 v[36:39], v[144:147], v[202:205], 0
	v_mfma_f32_16x16x32_bf16 v[32:35], v[176:179], v[202:205], 0
	v_mfma_f32_16x16x32_bf16 v[20:23], v[144:147], v[210:213], 0
	v_mfma_f32_16x16x32_bf16 v[16:19], v[176:179], v[210:213], 0
	v_mfma_f32_16x16x32_bf16 v[4:7], v[144:147], v[218:221], 0
	v_mfma_f32_16x16x32_bf16 v[0:3], v[176:179], v[218:221], 0
	s_setprio 0
	s_setprio 1
	v_mfma_f32_16x16x32_bf16 v[52:55], v[148:151], v[198:201], v[52:55]
	v_mfma_f32_16x16x32_bf16 v[48:51], v[180:183], v[198:201], v[48:51]
	v_mfma_f32_16x16x32_bf16 v[36:39], v[148:151], v[206:209], v[36:39]
	v_mfma_f32_16x16x32_bf16 v[32:35], v[180:183], v[206:209], v[32:35]
	v_mfma_f32_16x16x32_bf16 v[20:23], v[148:151], v[214:217], v[20:23]
	v_mfma_f32_16x16x32_bf16 v[16:19], v[180:183], v[214:217], v[16:19]
	v_mfma_f32_16x16x32_bf16 v[4:7], v[148:151], v[222:225], v[4:7]
	v_mfma_f32_16x16x32_bf16 v[0:3], v[180:183], v[222:225], v[0:3]
	s_barrier
	s_setprio 0
	s_branch .Lpeel_mid_p1
	s_nop 0
	s_nop 0
	s_nop 0
	s_nop 0
	s_nop 0
	s_nop 0
	s_nop 0
	s_nop 0
	s_nop 0
	s_nop 0
	s_nop 0
	s_nop 0
.LBB0_146:
	ds_read_b128 v[128:131], v188
	ds_read_b128 v[132:135], v188 offset:1024
	ds_read_b128 v[136:139], v188 offset:2048
	ds_read_b128 v[140:143], v188 offset:3072
	ds_read_b128 v[144:147], v189
	ds_read_b128 v[148:151], v189 offset:1024
	ds_read_b128 v[176:179], v189 offset:2048
	ds_read_b128 v[180:183], v189 offset:3072
	s_add_u32 s50, s48, 0x100
	s_addc_u32 s51, s49, 0
	s_cmp_eq_u32 s57, 28
	s_cselect_b32 s55, s21, s51
	s_cselect_b32 s54, s20, s50
	s_cselect_b32 s53, s23, s56
	s_cselect_b32 s52, s22, s27
	v_lshl_add_u64 v[184:185], s[48:49], 0, v[170:171]
	s_add_i32 m0, s60, 0xc000
	ds_read_b128 v[194:197], v190
	ds_read_b128 v[198:201], v190 offset:1024
	ds_read_b128 v[202:205], v190 offset:2048
	ds_read_b128 v[206:209], v190 offset:3072
	ds_read_b128 v[210:213], v190 offset:4096
	ds_read_b128 v[214:217], v190 offset:5120
	ds_read_b128 v[218:221], v190 offset:6144
	ds_read_b128 v[222:225], v190 offset:7168
	global_load_lds_dwordx4 v[184:185], off
	v_lshl_add_u64 v[184:185], s[48:49], 0, v[172:173]
	s_add_i32 m0, s60, 0xe000
	s_nop 0
	global_load_lds_dwordx4 v[184:185], off
	s_waitcnt vmcnt(8) lgkmcnt(0)
	s_setprio 1
	s_barrier
	v_mfma_f32_16x16x32_bf16 v[120:123], v[128:131], v[194:197], v[120:123]
	v_mfma_f32_16x16x32_bf16 v[124:127], v[136:139], v[194:197], v[124:127]
	v_mfma_f32_16x16x32_bf16 v[108:111], v[128:131], v[202:205], v[108:111]
	v_mfma_f32_16x16x32_bf16 v[104:107], v[136:139], v[202:205], v[104:107]
	v_mfma_f32_16x16x32_bf16 v[92:95], v[128:131], v[210:213], v[92:95]
	v_mfma_f32_16x16x32_bf16 v[88:91], v[136:139], v[210:213], v[88:91]
	v_mfma_f32_16x16x32_bf16 v[76:79], v[128:131], v[218:221], v[76:79]
	v_mfma_f32_16x16x32_bf16 v[72:75], v[136:139], v[218:221], v[72:75]
	s_setprio 0
	s_setprio 1
	v_mfma_f32_16x16x32_bf16 v[120:123], v[132:135], v[198:201], v[120:123]
	v_mfma_f32_16x16x32_bf16 v[124:127], v[140:143], v[198:201], v[124:127]
	v_mfma_f32_16x16x32_bf16 v[108:111], v[132:135], v[206:209], v[108:111]
	v_mfma_f32_16x16x32_bf16 v[104:107], v[140:143], v[206:209], v[104:107]
	v_mfma_f32_16x16x32_bf16 v[92:95], v[132:135], v[214:217], v[92:95]
	v_mfma_f32_16x16x32_bf16 v[88:91], v[140:143], v[214:217], v[88:91]
	v_mfma_f32_16x16x32_bf16 v[76:79], v[132:135], v[222:225], v[76:79]
	v_mfma_f32_16x16x32_bf16 v[72:75], v[140:143], v[222:225], v[72:75]
	s_setprio 0
	s_setprio 1
	v_mfma_f32_16x16x32_bf16 v[112:115], v[144:147], v[194:197], v[112:115]
	v_mfma_f32_16x16x32_bf16 v[116:119], v[176:179], v[194:197], v[116:119]
	v_mfma_f32_16x16x32_bf16 v[100:103], v[144:147], v[202:205], v[100:103]
	v_mfma_f32_16x16x32_bf16 v[96:99], v[176:179], v[202:205], v[96:99]
	v_mfma_f32_16x16x32_bf16 v[84:87], v[144:147], v[210:213], v[84:87]
	v_mfma_f32_16x16x32_bf16 v[80:83], v[176:179], v[210:213], v[80:83]
	v_mfma_f32_16x16x32_bf16 v[68:71], v[144:147], v[218:221], v[68:71]
	v_mfma_f32_16x16x32_bf16 v[64:67], v[176:179], v[218:221], v[64:67]
	s_setprio 0
	s_setprio 1
	v_mfma_f32_16x16x32_bf16 v[112:115], v[148:151], v[198:201], v[112:115]
	v_mfma_f32_16x16x32_bf16 v[116:119], v[180:183], v[198:201], v[116:119]
	v_mfma_f32_16x16x32_bf16 v[100:103], v[148:151], v[206:209], v[100:103]
	v_mfma_f32_16x16x32_bf16 v[96:99], v[180:183], v[206:209], v[96:99]
	v_mfma_f32_16x16x32_bf16 v[84:87], v[148:151], v[214:217], v[84:87]
	v_mfma_f32_16x16x32_bf16 v[80:83], v[180:183], v[214:217], v[80:83]
	v_mfma_f32_16x16x32_bf16 v[68:71], v[148:151], v[222:225], v[68:71]
	v_mfma_f32_16x16x32_bf16 v[64:67], v[180:183], v[222:225], v[64:67]
	s_barrier
	s_setprio 0
	s_add_i32 s48, s71, s3
	v_lshl_add_u64 v[184:185], s[52:53], 0, v[154:155]
	s_mov_b32 m0, s48
	ds_read_b128 v[194:197], v190 offset:16384
	ds_read_b128 v[198:201], v190 offset:17408
	ds_read_b128 v[202:205], v190 offset:18432
	ds_read_b128 v[206:209], v190 offset:19456
	ds_read_b128 v[210:213], v190 offset:20480
	ds_read_b128 v[214:217], v190 offset:21504
	ds_read_b128 v[218:221], v190 offset:22528
	ds_read_b128 v[222:225], v190 offset:23552
	global_load_lds_dwordx4 v[184:185], off
	s_add_i32 m0, s48, 0x2000
	s_add_u32 s48, s52, 0x80000
	v_lshl_add_u64 v[226:227], s[52:53], 0, v[158:159]
	s_addc_u32 s49, s53, 0
	s_add_i32 s58, s72, s3
	global_load_lds_dwordx4 v[226:227], off
	v_lshl_add_u64 v[228:229], s[48:49], 0, v[154:155]
	s_mov_b32 m0, s58
	v_lshl_add_u64 v[230:231], s[54:55], 0, v[156:157]
	global_load_lds_dwordx4 v[228:229], off
	v_lshl_add_u64 v[228:229], s[48:49], 0, v[158:159]
	s_add_i32 m0, s58, 0x2000
	s_nop 0
	global_load_lds_dwordx4 v[228:229], off
	v_lshl_add_u64 v[228:229], s[54:55], 0, v[152:153]
	s_mov_b32 m0, s60
	s_nop 0
	global_load_lds_dwordx4 v[228:229], off
	s_mov_b32 m0, s61
	s_nop 0
	global_load_lds_dwordx4 v[230:231], off
	s_waitcnt vmcnt(8) lgkmcnt(0)
	s_setprio 1
	s_barrier
	v_mfma_f32_16x16x32_bf16 v[60:63], v[128:131], v[194:197], v[60:63]
	v_mfma_f32_16x16x32_bf16 v[56:59], v[136:139], v[194:197], v[56:59]
	v_mfma_f32_16x16x32_bf16 v[44:47], v[128:131], v[202:205], v[44:47]
	v_mfma_f32_16x16x32_bf16 v[40:43], v[136:139], v[202:205], v[40:43]
	v_mfma_f32_16x16x32_bf16 v[28:31], v[128:131], v[210:213], v[28:31]
	v_mfma_f32_16x16x32_bf16 v[24:27], v[136:139], v[210:213], v[24:27]
	v_mfma_f32_16x16x32_bf16 v[12:15], v[128:131], v[218:221], v[12:15]
	v_mfma_f32_16x16x32_bf16 v[8:11], v[136:139], v[218:221], v[8:11]
	s_setprio 0
	s_setprio 1
	v_mfma_f32_16x16x32_bf16 v[60:63], v[132:135], v[198:201], v[60:63]
	v_mfma_f32_16x16x32_bf16 v[56:59], v[140:143], v[198:201], v[56:59]
	v_mfma_f32_16x16x32_bf16 v[44:47], v[132:135], v[206:209], v[44:47]
	v_mfma_f32_16x16x32_bf16 v[40:43], v[140:143], v[206:209], v[40:43]
	v_mfma_f32_16x16x32_bf16 v[28:31], v[132:135], v[214:217], v[28:31]
	v_mfma_f32_16x16x32_bf16 v[24:27], v[140:143], v[214:217], v[24:27]
	v_mfma_f32_16x16x32_bf16 v[12:15], v[132:135], v[222:225], v[12:15]
	v_mfma_f32_16x16x32_bf16 v[8:11], v[140:143], v[222:225], v[8:11]
	s_setprio 0
	s_setprio 1
	v_mfma_f32_16x16x32_bf16 v[52:55], v[144:147], v[194:197], v[52:55]
	v_mfma_f32_16x16x32_bf16 v[48:51], v[176:179], v[194:197], v[48:51]
	v_mfma_f32_16x16x32_bf16 v[36:39], v[144:147], v[202:205], v[36:39]
	v_mfma_f32_16x16x32_bf16 v[32:35], v[176:179], v[202:205], v[32:35]
	v_mfma_f32_16x16x32_bf16 v[20:23], v[144:147], v[210:213], v[20:23]
	v_mfma_f32_16x16x32_bf16 v[16:19], v[176:179], v[210:213], v[16:19]
	v_mfma_f32_16x16x32_bf16 v[4:7], v[144:147], v[218:221], v[4:7]
	v_mfma_f32_16x16x32_bf16 v[0:3], v[176:179], v[218:221], v[0:3]
	s_setprio 0
	s_setprio 1
	v_mfma_f32_16x16x32_bf16 v[52:55], v[148:151], v[198:201], v[52:55]
	v_mfma_f32_16x16x32_bf16 v[48:51], v[180:183], v[198:201], v[48:51]
	v_mfma_f32_16x16x32_bf16 v[36:39], v[148:151], v[206:209], v[36:39]
	v_mfma_f32_16x16x32_bf16 v[32:35], v[180:183], v[206:209], v[32:35]
	v_mfma_f32_16x16x32_bf16 v[20:23], v[148:151], v[214:217], v[20:23]
	v_mfma_f32_16x16x32_bf16 v[16:19], v[180:183], v[214:217], v[16:19]
	v_mfma_f32_16x16x32_bf16 v[4:7], v[148:151], v[222:225], v[4:7]
	v_mfma_f32_16x16x32_bf16 v[0:3], v[180:183], v[222:225], v[0:3]
	s_barrier
	s_setprio 0
.Lpeel_mid_p1:
	s_add_i32 s58, 0, 0x18000
	s_add_i32 s59, 0, 0x1c000
	v_add_u32_e32 v140, s58, v186
	v_add_u32_e32 v160, s59, v186
	ds_read_b128 v[128:131], v140
	ds_read_b128 v[132:135], v140 offset:1024
	ds_read_b128 v[136:139], v140 offset:2048
	ds_read_b128 v[140:143], v140 offset:3072
	ds_read_b128 v[144:147], v160
	ds_read_b128 v[148:151], v160 offset:1024
	ds_read_b128 v[176:179], v160 offset:2048
	ds_read_b128 v[180:183], v160 offset:3072
	s_add_u32 s48, s54, 0xa0000
	s_addc_u32 s49, s55, 0
	s_mov_b32 m0, s62
	v_lshl_add_u64 v[232:233], s[48:49], 0, v[152:153]
	ds_read_b128 v[194:197], v190 offset:32768
	ds_read_b128 v[198:201], v190 offset:33792
	ds_read_b128 v[202:205], v190 offset:34816
	ds_read_b128 v[206:209], v190 offset:35840
	ds_read_b128 v[210:213], v190 offset:36864
	ds_read_b128 v[214:217], v190 offset:37888
	ds_read_b128 v[218:221], v190 offset:38912
	ds_read_b128 v[222:225], v190 offset:39936
	global_load_lds_dwordx4 v[232:233], off
	v_lshl_add_u64 v[232:233], s[48:49], 0, v[156:157]
	s_mov_b32 m0, s63
	s_nop 0
	global_load_lds_dwordx4 v[232:233], off
	s_waitcnt vmcnt(8) lgkmcnt(0)
	s_setprio 1
	s_barrier
	v_mfma_f32_16x16x32_bf16 v[120:123], v[128:131], v[194:197], v[120:123]
	v_mfma_f32_16x16x32_bf16 v[124:127], v[136:139], v[194:197], v[124:127]
	v_mfma_f32_16x16x32_bf16 v[108:111], v[128:131], v[202:205], v[108:111]
	v_mfma_f32_16x16x32_bf16 v[104:107], v[136:139], v[202:205], v[104:107]
	v_mfma_f32_16x16x32_bf16 v[92:95], v[128:131], v[210:213], v[92:95]
	v_mfma_f32_16x16x32_bf16 v[88:91], v[136:139], v[210:213], v[88:91]
	v_mfma_f32_16x16x32_bf16 v[76:79], v[128:131], v[218:221], v[76:79]
	v_mfma_f32_16x16x32_bf16 v[72:75], v[136:139], v[218:221], v[72:75]
	s_setprio 0
	s_setprio 1
	v_mfma_f32_16x16x32_bf16 v[120:123], v[132:135], v[198:201], v[120:123]
	v_mfma_f32_16x16x32_bf16 v[124:127], v[140:143], v[198:201], v[124:127]
	v_mfma_f32_16x16x32_bf16 v[108:111], v[132:135], v[206:209], v[108:111]
	v_mfma_f32_16x16x32_bf16 v[104:107], v[140:143], v[206:209], v[104:107]
	v_mfma_f32_16x16x32_bf16 v[92:95], v[132:135], v[214:217], v[92:95]
	v_mfma_f32_16x16x32_bf16 v[88:91], v[140:143], v[214:217], v[88:91]
	v_mfma_f32_16x16x32_bf16 v[76:79], v[132:135], v[222:225], v[76:79]
	v_mfma_f32_16x16x32_bf16 v[72:75], v[140:143], v[222:225], v[72:75]
	s_setprio 0
	s_setprio 1
	v_mfma_f32_16x16x32_bf16 v[112:115], v[144:147], v[194:197], v[112:115]
	v_mfma_f32_16x16x32_bf16 v[116:119], v[176:179], v[194:197], v[116:119]
	v_mfma_f32_16x16x32_bf16 v[100:103], v[144:147], v[202:205], v[100:103]
	v_mfma_f32_16x16x32_bf16 v[96:99], v[176:179], v[202:205], v[96:99]
	v_mfma_f32_16x16x32_bf16 v[84:87], v[144:147], v[210:213], v[84:87]
	v_mfma_f32_16x16x32_bf16 v[80:83], v[176:179], v[210:213], v[80:83]
	v_mfma_f32_16x16x32_bf16 v[68:71], v[144:147], v[218:221], v[68:71]
	v_mfma_f32_16x16x32_bf16 v[64:67], v[176:179], v[218:221], v[64:67]
	s_setprio 0
	s_setprio 1
	v_mfma_f32_16x16x32_bf16 v[112:115], v[148:151], v[198:201], v[112:115]
	v_mfma_f32_16x16x32_bf16 v[116:119], v[180:183], v[198:201], v[116:119]
	v_mfma_f32_16x16x32_bf16 v[100:103], v[148:151], v[206:209], v[100:103]
	v_mfma_f32_16x16x32_bf16 v[96:99], v[180:183], v[206:209], v[96:99]
	v_mfma_f32_16x16x32_bf16 v[84:87], v[148:151], v[214:217], v[84:87]
	v_mfma_f32_16x16x32_bf16 v[80:83], v[180:183], v[214:217], v[80:83]
	v_mfma_f32_16x16x32_bf16 v[68:71], v[148:151], v[222:225], v[68:71]
	v_mfma_f32_16x16x32_bf16 v[64:67], v[180:183], v[222:225], v[64:67]
	s_barrier
	s_setprio 0
	s_add_i32 s48, s58, s3
	v_lshl_add_u64 v[184:185], v[184:185], 0, s[14:15]
	s_mov_b32 m0, s48
	ds_read_b128 v[194:197], v190 offset:49152
	ds_read_b128 v[198:201], v190 offset:50176
	ds_read_b128 v[202:205], v190 offset:51200
	ds_read_b128 v[206:209], v190 offset:52224
	ds_read_b128 v[210:213], v190 offset:53248
	ds_read_b128 v[214:217], v190 offset:54272
	ds_read_b128 v[218:221], v190 offset:55296
	ds_read_b128 v[222:225], v190 offset:56320
	global_load_lds_dwordx4 v[184:185], off
	s_add_i32 m0, s48, 0x2000
	s_add_u32 s48, s52, 0x80080
	v_lshl_add_u64 v[184:185], v[226:227], 0, s[14:15]
	s_addc_u32 s49, s53, 0
	s_add_i32 s52, s59, s3
	global_load_lds_dwordx4 v[184:185], off
	v_lshl_add_u64 v[184:185], s[48:49], 0, v[154:155]
	s_mov_b32 m0, s52
	s_nop 0
	global_load_lds_dwordx4 v[184:185], off
	v_lshl_add_u64 v[184:185], s[48:49], 0, v[158:159]
	s_add_i32 m0, s52, 0x2000
	s_nop 0
	global_load_lds_dwordx4 v[184:185], off
	v_lshl_add_u64 v[184:185], v[228:229], 0, s[14:15]
	s_mov_b32 m0, s66
	s_nop 0
	global_load_lds_dwordx4 v[184:185], off
	v_lshl_add_u64 v[184:185], v[230:231], 0, s[14:15]
	s_mov_b32 m0, s67
	s_nop 0
	global_load_lds_dwordx4 v[184:185], off
	s_waitcnt vmcnt(8) lgkmcnt(0)
	s_setprio 1
	s_barrier
	v_mfma_f32_16x16x32_bf16 v[60:63], v[128:131], v[194:197], v[60:63]
	v_mfma_f32_16x16x32_bf16 v[56:59], v[136:139], v[194:197], v[56:59]
	v_mfma_f32_16x16x32_bf16 v[44:47], v[128:131], v[202:205], v[44:47]
	v_mfma_f32_16x16x32_bf16 v[40:43], v[136:139], v[202:205], v[40:43]
	v_mfma_f32_16x16x32_bf16 v[28:31], v[128:131], v[210:213], v[28:31]
	v_mfma_f32_16x16x32_bf16 v[24:27], v[136:139], v[210:213], v[24:27]
	v_mfma_f32_16x16x32_bf16 v[12:15], v[128:131], v[218:221], v[12:15]
	v_mfma_f32_16x16x32_bf16 v[8:11], v[136:139], v[218:221], v[8:11]
	s_setprio 0
	s_setprio 1
	v_mfma_f32_16x16x32_bf16 v[60:63], v[132:135], v[198:201], v[60:63]
	v_mfma_f32_16x16x32_bf16 v[56:59], v[140:143], v[198:201], v[56:59]
	v_mfma_f32_16x16x32_bf16 v[44:47], v[132:135], v[206:209], v[44:47]
	v_mfma_f32_16x16x32_bf16 v[40:43], v[140:143], v[206:209], v[40:43]
	v_mfma_f32_16x16x32_bf16 v[28:31], v[132:135], v[214:217], v[28:31]
	v_mfma_f32_16x16x32_bf16 v[24:27], v[140:143], v[214:217], v[24:27]
	v_mfma_f32_16x16x32_bf16 v[12:15], v[132:135], v[222:225], v[12:15]
	v_mfma_f32_16x16x32_bf16 v[8:11], v[140:143], v[222:225], v[8:11]
	s_setprio 0
	s_setprio 1
	v_mfma_f32_16x16x32_bf16 v[52:55], v[144:147], v[194:197], v[52:55]
	v_mfma_f32_16x16x32_bf16 v[48:51], v[176:179], v[194:197], v[48:51]
	v_mfma_f32_16x16x32_bf16 v[36:39], v[144:147], v[202:205], v[36:39]
	v_mfma_f32_16x16x32_bf16 v[32:35], v[176:179], v[202:205], v[32:35]
	s_add_i32 s57, s57, 2
	v_mfma_f32_16x16x32_bf16 v[20:23], v[144:147], v[210:213], v[20:23]
	s_add_u32 s27, s27, 0x100
	v_mfma_f32_16x16x32_bf16 v[16:19], v[176:179], v[210:213], v[16:19]
	s_addc_u32 s56, s56, 0
	v_mfma_f32_16x16x32_bf16 v[4:7], v[144:147], v[218:221], v[4:7]
	s_cmp_gt_u32 s57, 29
	v_mfma_f32_16x16x32_bf16 v[0:3], v[176:179], v[218:221], v[0:3]
	s_setprio 0
	s_setprio 1
	s_mov_b64 s[48:49], s[50:51]
	v_mfma_f32_16x16x32_bf16 v[52:55], v[148:151], v[198:201], v[52:55]
	v_mfma_f32_16x16x32_bf16 v[48:51], v[180:183], v[198:201], v[48:51]
	v_mfma_f32_16x16x32_bf16 v[36:39], v[148:151], v[206:209], v[36:39]
	v_mfma_f32_16x16x32_bf16 v[32:35], v[180:183], v[206:209], v[32:35]
	v_mfma_f32_16x16x32_bf16 v[20:23], v[148:151], v[214:217], v[20:23]
	v_mfma_f32_16x16x32_bf16 v[16:19], v[180:183], v[214:217], v[16:19]
	v_mfma_f32_16x16x32_bf16 v[4:7], v[148:151], v[222:225], v[4:7]
	v_mfma_f32_16x16x32_bf16 v[0:3], v[180:183], v[222:225], v[0:3]
	s_barrier
	s_setprio 0
	s_cbranch_scc0 .LBB0_146
	s_and_b64 vcc, exec, s[18:19]
	s_cbranch_vccz .LBB0_149
	s_barrier

.LBB0_250:
	ds_read_b128 v[148:151], v142
	ds_read_b128 v[152:155], v142 offset:1024
	ds_read_b128 v[156:159], v142 offset:2048
	ds_read_b128 v[160:163], v142 offset:3072
	ds_read_b128 v[164:167], v143
	ds_read_b128 v[168:171], v143 offset:1024
	ds_read_b128 v[176:179], v143 offset:2048
	ds_read_b128 v[180:183], v143 offset:3072
	s_add_i32 s20, s18, 0xf4f60080
	s_cmp_lg_u32 s52, 28
	s_cselect_b32 s20, s20, 0
	s_add_u32 s22, s2, s20
	s_addc_u32 s23, s3, 0
	s_add_u32 s20, s12, s20
	s_addc_u32 s21, s13, 0
	s_mov_b32 m0, s53
	v_lshl_add_u64 v[172:173], v[138:139], 0, s[18:19]
	ds_read_b128 v[188:191], v144
	ds_read_b128 v[192:195], v144 offset:1024
	ds_read_b128 v[196:199], v144 offset:2048
	ds_read_b128 v[200:203], v144 offset:3072
	ds_read_b128 v[204:207], v144 offset:4096
	ds_read_b128 v[208:211], v144 offset:5120
	ds_read_b128 v[212:215], v144 offset:6144
	ds_read_b128 v[216:219], v144 offset:7168
	global_load_lds_dwordx4 v[172:173], off
	v_lshl_add_u64 v[172:173], v[140:141], 0, s[18:19]
	s_mov_b32 m0, s54
	s_nop 0
	global_load_lds_dwordx4 v[172:173], off
	s_waitcnt vmcnt(8) lgkmcnt(0)
	s_setprio 1
	s_barrier
	v_mfma_f32_16x16x32_bf16 v[124:127], v[148:151], v[188:191], v[124:127]
	v_mfma_f32_16x16x32_bf16 v[120:123], v[156:159], v[188:191], v[120:123]
	v_mfma_f32_16x16x32_bf16 v[116:119], v[148:151], v[196:199], v[116:119]
	v_mfma_f32_16x16x32_bf16 v[112:115], v[156:159], v[196:199], v[112:115]
	v_mfma_f32_16x16x32_bf16 v[100:103], v[148:151], v[204:207], v[100:103]
	v_mfma_f32_16x16x32_bf16 v[96:99], v[156:159], v[204:207], v[96:99]
	v_mfma_f32_16x16x32_bf16 v[84:87], v[148:151], v[212:215], v[84:87]
	v_mfma_f32_16x16x32_bf16 v[80:83], v[156:159], v[212:215], v[80:83]
	s_setprio 0
	s_setprio 1
	v_mfma_f32_16x16x32_bf16 v[124:127], v[152:155], v[192:195], v[124:127]
	v_mfma_f32_16x16x32_bf16 v[120:123], v[160:163], v[192:195], v[120:123]
	v_mfma_f32_16x16x32_bf16 v[116:119], v[152:155], v[200:203], v[116:119]
	v_mfma_f32_16x16x32_bf16 v[112:115], v[160:163], v[200:203], v[112:115]
	v_mfma_f32_16x16x32_bf16 v[100:103], v[152:155], v[208:211], v[100:103]
	v_mfma_f32_16x16x32_bf16 v[96:99], v[160:163], v[208:211], v[96:99]
	v_mfma_f32_16x16x32_bf16 v[84:87], v[152:155], v[216:219], v[84:87]
	v_mfma_f32_16x16x32_bf16 v[80:83], v[160:163], v[216:219], v[80:83]
	s_setprio 0
	s_setprio 1
	v_mfma_f32_16x16x32_bf16 v[108:111], v[164:167], v[188:191], v[108:111]
	v_mfma_f32_16x16x32_bf16 v[104:107], v[176:179], v[188:191], v[104:107]
	v_mfma_f32_16x16x32_bf16 v[92:95], v[164:167], v[196:199], v[92:95]
	v_mfma_f32_16x16x32_bf16 v[88:91], v[176:179], v[196:199], v[88:91]
	v_mfma_f32_16x16x32_bf16 v[76:79], v[164:167], v[204:207], v[76:79]
	v_mfma_f32_16x16x32_bf16 v[72:75], v[176:179], v[204:207], v[72:75]
	v_mfma_f32_16x16x32_bf16 v[68:71], v[164:167], v[212:215], v[68:71]
	v_mfma_f32_16x16x32_bf16 v[64:67], v[176:179], v[212:215], v[64:67]
	s_setprio 0
	s_setprio 1
	v_mfma_f32_16x16x32_bf16 v[108:111], v[168:171], v[192:195], v[108:111]
	v_mfma_f32_16x16x32_bf16 v[104:107], v[180:183], v[192:195], v[104:107]
	v_mfma_f32_16x16x32_bf16 v[92:95], v[168:171], v[200:203], v[92:95]
	v_mfma_f32_16x16x32_bf16 v[88:91], v[180:183], v[200:203], v[88:91]
	v_mfma_f32_16x16x32_bf16 v[76:79], v[168:171], v[208:211], v[76:79]
	v_mfma_f32_16x16x32_bf16 v[72:75], v[180:183], v[208:211], v[72:75]
	v_mfma_f32_16x16x32_bf16 v[68:71], v[168:171], v[216:219], v[68:71]
	v_mfma_f32_16x16x32_bf16 v[64:67], v[180:183], v[216:219], v[64:67]
	s_barrier
	s_setprio 0
	s_mov_b32 m0, s55
	v_lshl_add_u64 v[172:173], s[20:21], 0, v[132:133]
	s_add_u32 s64, s20, 0x80000
	ds_read_b128 v[188:191], v144 offset:16384
	ds_read_b128 v[192:195], v144 offset:17408
	ds_read_b128 v[196:199], v144 offset:18432
	ds_read_b128 v[200:203], v144 offset:19456
	ds_read_b128 v[204:207], v144 offset:20480
	ds_read_b128 v[208:211], v144 offset:21504
	ds_read_b128 v[212:215], v144 offset:22528
	ds_read_b128 v[216:219], v144 offset:23552
	global_load_lds_dwordx4 v[172:173], off
	v_lshl_add_u64 v[184:185], s[20:21], 0, v[128:129]
	s_mov_b32 m0, s56
	s_addc_u32 s65, s21, 0
	global_load_lds_dwordx4 v[184:185], off
	v_lshl_add_u64 v[220:221], s[64:65], 0, v[132:133]
	s_mov_b32 m0, s57
	v_lshl_add_u64 v[222:223], s[22:23], 0, v[130:131]
	global_load_lds_dwordx4 v[220:221], off
	v_lshl_add_u64 v[220:221], s[64:65], 0, v[128:129]
	s_mov_b32 m0, s58
	s_nop 0
	global_load_lds_dwordx4 v[220:221], off
	v_lshl_add_u64 v[220:221], s[22:23], 0, v[134:135]
	s_mov_b32 m0, s1
	s_nop 0
	global_load_lds_dwordx4 v[220:221], off
	s_mov_b32 m0, s26
	s_nop 0
	global_load_lds_dwordx4 v[222:223], off
	s_waitcnt vmcnt(8) lgkmcnt(0)
	s_setprio 1
	s_barrier
	v_mfma_f32_16x16x32_bf16 v[60:63], v[148:151], v[188:191], v[60:63]
	v_mfma_f32_16x16x32_bf16 v[56:59], v[156:159], v[188:191], v[56:59]
	v_mfma_f32_16x16x32_bf16 v[52:55], v[148:151], v[196:199], v[52:55]
	v_mfma_f32_16x16x32_bf16 v[48:51], v[156:159], v[196:199], v[48:51]
	v_mfma_f32_16x16x32_bf16 v[36:39], v[148:151], v[204:207], v[36:39]
	v_mfma_f32_16x16x32_bf16 v[32:35], v[156:159], v[204:207], v[32:35]
	v_mfma_f32_16x16x32_bf16 v[20:23], v[148:151], v[212:215], v[20:23]
	v_mfma_f32_16x16x32_bf16 v[16:19], v[156:159], v[212:215], v[16:19]
	s_setprio 0
	s_setprio 1
	v_mfma_f32_16x16x32_bf16 v[60:63], v[152:155], v[192:195], v[60:63]
	v_mfma_f32_16x16x32_bf16 v[56:59], v[160:163], v[192:195], v[56:59]
	v_mfma_f32_16x16x32_bf16 v[52:55], v[152:155], v[200:203], v[52:55]
	v_mfma_f32_16x16x32_bf16 v[48:51], v[160:163], v[200:203], v[48:51]
	v_mfma_f32_16x16x32_bf16 v[36:39], v[152:155], v[208:211], v[36:39]
	v_mfma_f32_16x16x32_bf16 v[32:35], v[160:163], v[208:211], v[32:35]
	v_mfma_f32_16x16x32_bf16 v[20:23], v[152:155], v[216:219], v[20:23]
	v_mfma_f32_16x16x32_bf16 v[16:19], v[160:163], v[216:219], v[16:19]
	s_setprio 0
	s_setprio 1
	v_mfma_f32_16x16x32_bf16 v[44:47], v[164:167], v[188:191], v[44:47]
	v_mfma_f32_16x16x32_bf16 v[40:43], v[176:179], v[188:191], v[40:43]
	v_mfma_f32_16x16x32_bf16 v[28:31], v[164:167], v[196:199], v[28:31]
	v_mfma_f32_16x16x32_bf16 v[24:27], v[176:179], v[196:199], v[24:27]
	v_mfma_f32_16x16x32_bf16 v[12:15], v[164:167], v[204:207], v[12:15]
	v_mfma_f32_16x16x32_bf16 v[8:11], v[176:179], v[204:207], v[8:11]
	v_mfma_f32_16x16x32_bf16 v[4:7], v[164:167], v[212:215], v[4:7]
	v_mfma_f32_16x16x32_bf16 v[0:3], v[176:179], v[212:215], v[0:3]
	s_setprio 0
	s_setprio 1
	v_mfma_f32_16x16x32_bf16 v[44:47], v[168:171], v[192:195], v[44:47]
	v_mfma_f32_16x16x32_bf16 v[40:43], v[180:183], v[192:195], v[40:43]
	v_mfma_f32_16x16x32_bf16 v[28:31], v[168:171], v[200:203], v[28:31]
	v_mfma_f32_16x16x32_bf16 v[24:27], v[180:183], v[200:203], v[24:27]
	v_mfma_f32_16x16x32_bf16 v[12:15], v[168:171], v[208:211], v[12:15]
	v_mfma_f32_16x16x32_bf16 v[8:11], v[180:183], v[208:211], v[8:11]
	v_mfma_f32_16x16x32_bf16 v[4:7], v[168:171], v[216:219], v[4:7]
	v_mfma_f32_16x16x32_bf16 v[0:3], v[180:183], v[216:219], v[0:3]
	s_barrier
	s_setprio 0
	ds_read_b128 v[148:151], v145
	ds_read_b128 v[152:155], v145 offset:1024
	ds_read_b128 v[156:159], v145 offset:2048
	ds_read_b128 v[160:163], v145 offset:3072
	ds_read_b128 v[164:167], v146
	ds_read_b128 v[168:171], v146 offset:1024
	ds_read_b128 v[176:179], v146 offset:2048
	ds_read_b128 v[180:183], v146 offset:3072
	s_add_u32 s22, s22, 0xa0000
	s_addc_u32 s23, s23, 0
	s_mov_b32 m0, s27
	v_lshl_add_u64 v[224:225], s[22:23], 0, v[134:135]
	ds_read_b128 v[188:191], v144 offset:32768
	ds_read_b128 v[192:195], v144 offset:33792
	ds_read_b128 v[196:199], v144 offset:34816
	ds_read_b128 v[200:203], v144 offset:35840
	ds_read_b128 v[204:207], v144 offset:36864
	ds_read_b128 v[208:211], v144 offset:37888
	ds_read_b128 v[212:215], v144 offset:38912
	ds_read_b128 v[216:219], v144 offset:39936
	global_load_lds_dwordx4 v[224:225], off
	v_lshl_add_u64 v[224:225], s[22:23], 0, v[130:131]
	s_mov_b32 m0, s48
	s_nop 0
	global_load_lds_dwordx4 v[224:225], off
	s_waitcnt vmcnt(8) lgkmcnt(0)
	s_setprio 1
	s_barrier
	v_mfma_f32_16x16x32_bf16 v[124:127], v[148:151], v[188:191], v[124:127]
	v_mfma_f32_16x16x32_bf16 v[120:123], v[156:159], v[188:191], v[120:123]
	v_mfma_f32_16x16x32_bf16 v[116:119], v[148:151], v[196:199], v[116:119]
	v_mfma_f32_16x16x32_bf16 v[112:115], v[156:159], v[196:199], v[112:115]
	v_mfma_f32_16x16x32_bf16 v[100:103], v[148:151], v[204:207], v[100:103]
	v_mfma_f32_16x16x32_bf16 v[96:99], v[156:159], v[204:207], v[96:99]
	v_mfma_f32_16x16x32_bf16 v[84:87], v[148:151], v[212:215], v[84:87]
	v_mfma_f32_16x16x32_bf16 v[80:83], v[156:159], v[212:215], v[80:83]
	s_setprio 0
	s_setprio 1
	v_mfma_f32_16x16x32_bf16 v[124:127], v[152:155], v[192:195], v[124:127]
	v_mfma_f32_16x16x32_bf16 v[120:123], v[160:163], v[192:195], v[120:123]
	v_mfma_f32_16x16x32_bf16 v[116:119], v[152:155], v[200:203], v[116:119]
	v_mfma_f32_16x16x32_bf16 v[112:115], v[160:163], v[200:203], v[112:115]
	v_mfma_f32_16x16x32_bf16 v[100:103], v[152:155], v[208:211], v[100:103]
	v_mfma_f32_16x16x32_bf16 v[96:99], v[160:163], v[208:211], v[96:99]
	v_mfma_f32_16x16x32_bf16 v[84:87], v[152:155], v[216:219], v[84:87]
	v_mfma_f32_16x16x32_bf16 v[80:83], v[160:163], v[216:219], v[80:83]
	s_setprio 0
	s_setprio 1
	v_mfma_f32_16x16x32_bf16 v[108:111], v[164:167], v[188:191], v[108:111]
	v_mfma_f32_16x16x32_bf16 v[104:107], v[176:179], v[188:191], v[104:107]
	v_mfma_f32_16x16x32_bf16 v[92:95], v[164:167], v[196:199], v[92:95]
	v_mfma_f32_16x16x32_bf16 v[88:91], v[176:179], v[196:199], v[88:91]
	v_mfma_f32_16x16x32_bf16 v[76:79], v[164:167], v[204:207], v[76:79]
	v_mfma_f32_16x16x32_bf16 v[72:75], v[176:179], v[204:207], v[72:75]
	v_mfma_f32_16x16x32_bf16 v[68:71], v[164:167], v[212:215], v[68:71]
	v_mfma_f32_16x16x32_bf16 v[64:67], v[176:179], v[212:215], v[64:67]
	s_setprio 0
	s_setprio 1
	v_mfma_f32_16x16x32_bf16 v[108:111], v[168:171], v[192:195], v[108:111]
	v_mfma_f32_16x16x32_bf16 v[104:107], v[180:183], v[192:195], v[104:107]
	v_mfma_f32_16x16x32_bf16 v[92:95], v[168:171], v[200:203], v[92:95]
	v_mfma_f32_16x16x32_bf16 v[88:91], v[180:183], v[200:203], v[88:91]
	v_mfma_f32_16x16x32_bf16 v[76:79], v[168:171], v[208:211], v[76:79]
	v_mfma_f32_16x16x32_bf16 v[72:75], v[180:183], v[208:211], v[72:75]
	v_mfma_f32_16x16x32_bf16 v[68:71], v[168:171], v[216:219], v[68:71]
	v_mfma_f32_16x16x32_bf16 v[64:67], v[180:183], v[216:219], v[64:67]
	s_barrier
	s_setprio 0
	s_mov_b32 m0, s59
	v_lshl_add_u64 v[172:173], v[172:173], 0, s[14:15]
	s_add_u32 s20, s20, 0x80080
	ds_read_b128 v[188:191], v144 offset:49152
	ds_read_b128 v[192:195], v144 offset:50176
	ds_read_b128 v[196:199], v144 offset:51200
	ds_read_b128 v[200:203], v144 offset:52224
	ds_read_b128 v[204:207], v144 offset:53248
	ds_read_b128 v[208:211], v144 offset:54272
	ds_read_b128 v[212:215], v144 offset:55296
	ds_read_b128 v[216:219], v144 offset:56320
	global_load_lds_dwordx4 v[172:173], off
	v_lshl_add_u64 v[172:173], v[184:185], 0, s[14:15]
	s_mov_b32 m0, s60
	s_addc_u32 s21, s21, 0
	global_load_lds_dwordx4 v[172:173], off
	v_lshl_add_u64 v[172:173], s[20:21], 0, v[132:133]
	s_mov_b32 m0, s61
	s_nop 0
	global_load_lds_dwordx4 v[172:173], off
	v_lshl_add_u64 v[172:173], s[20:21], 0, v[128:129]
	s_mov_b32 m0, s62
	s_nop 0
	global_load_lds_dwordx4 v[172:173], off
	v_lshl_add_u64 v[172:173], v[220:221], 0, s[14:15]
	s_mov_b32 m0, s50
	s_nop 0
	global_load_lds_dwordx4 v[172:173], off
	v_lshl_add_u64 v[172:173], v[222:223], 0, s[14:15]
	s_mov_b32 m0, s51
	s_nop 0
	global_load_lds_dwordx4 v[172:173], off
	s_waitcnt vmcnt(8) lgkmcnt(0)
	s_setprio 1
	s_barrier
	v_mfma_f32_16x16x32_bf16 v[60:63], v[148:151], v[188:191], v[60:63]
	v_mfma_f32_16x16x32_bf16 v[56:59], v[156:159], v[188:191], v[56:59]
	v_mfma_f32_16x16x32_bf16 v[52:55], v[148:151], v[196:199], v[52:55]
	v_mfma_f32_16x16x32_bf16 v[48:51], v[156:159], v[196:199], v[48:51]
	v_mfma_f32_16x16x32_bf16 v[36:39], v[148:151], v[204:207], v[36:39]
	v_mfma_f32_16x16x32_bf16 v[32:35], v[156:159], v[204:207], v[32:35]
	v_mfma_f32_16x16x32_bf16 v[20:23], v[148:151], v[212:215], v[20:23]
	v_mfma_f32_16x16x32_bf16 v[16:19], v[156:159], v[212:215], v[16:19]
	s_setprio 0
	s_setprio 1
	v_mfma_f32_16x16x32_bf16 v[60:63], v[152:155], v[192:195], v[60:63]
	v_mfma_f32_16x16x32_bf16 v[56:59], v[160:163], v[192:195], v[56:59]
	v_mfma_f32_16x16x32_bf16 v[52:55], v[152:155], v[200:203], v[52:55]
	v_mfma_f32_16x16x32_bf16 v[48:51], v[160:163], v[200:203], v[48:51]
	v_mfma_f32_16x16x32_bf16 v[36:39], v[152:155], v[208:211], v[36:39]
	v_mfma_f32_16x16x32_bf16 v[32:35], v[160:163], v[208:211], v[32:35]
	v_mfma_f32_16x16x32_bf16 v[20:23], v[152:155], v[216:219], v[20:23]
	v_mfma_f32_16x16x32_bf16 v[16:19], v[160:163], v[216:219], v[16:19]
	s_setprio 0
	s_setprio 1
	v_mfma_f32_16x16x32_bf16 v[44:47], v[164:167], v[188:191], v[44:47]
	v_mfma_f32_16x16x32_bf16 v[40:43], v[176:179], v[188:191], v[40:43]
	v_mfma_f32_16x16x32_bf16 v[28:31], v[164:167], v[196:199], v[28:31]
	v_mfma_f32_16x16x32_bf16 v[24:27], v[176:179], v[196:199], v[24:27]
	v_mfma_f32_16x16x32_bf16 v[12:15], v[164:167], v[204:207], v[12:15]
	v_mfma_f32_16x16x32_bf16 v[8:11], v[176:179], v[204:207], v[8:11]
	v_mfma_f32_16x16x32_bf16 v[4:7], v[164:167], v[212:215], v[4:7]
	v_mfma_f32_16x16x32_bf16 v[0:3], v[176:179], v[212:215], v[0:3]
	s_setprio 0
	s_setprio 1
	v_mfma_f32_16x16x32_bf16 v[44:47], v[168:171], v[192:195], v[44:47]
	v_mfma_f32_16x16x32_bf16 v[40:43], v[180:183], v[192:195], v[40:43]
	v_mfma_f32_16x16x32_bf16 v[28:31], v[168:171], v[200:203], v[28:31]
	v_mfma_f32_16x16x32_bf16 v[24:27], v[180:183], v[200:203], v[24:27]
	v_mfma_f32_16x16x32_bf16 v[12:15], v[168:171], v[208:211], v[12:15]
	v_mfma_f32_16x16x32_bf16 v[8:11], v[180:183], v[208:211], v[8:11]
	v_mfma_f32_16x16x32_bf16 v[4:7], v[168:171], v[216:219], v[4:7]
	v_mfma_f32_16x16x32_bf16 v[0:3], v[180:183], v[216:219], v[0:3]
	s_barrier
	s_setprio 0
	s_add_i32 s52, s52, 2
	s_add_u32 s18, s18, 0x100
	s_addc_u32 s19, s19, 0
	s_cmp_gt_u32 s52, 29
	s_cbranch_scc0 .LBB0_250
	s_cmpk_lt_u32 s24, 0x100
	s_cbranch_scc0 .LBB0_253
	s_barrier

.LBB0_596:
	s_lshl_b32 s98, s56, 3
	s_add_i32 s98, s98, s2
	s_mul_i32 s98, s98, 3
	v_lshl_add_u32 v164, s56, 8, v172
	s_cmp_eq_u32 s87, 3
	v_mad_i64_i32 v[162:163], s[56:57], v164, s77, v[156:157]
	s_cselect_b64 s[62:63], -1, 0
	s_lshl_b32 s56, s2, 8
	s_ashr_i32 s57, s56, 31
	v_lshl_add_u64 v[2:3], s[56:57], 1, v[162:163]
	s_mov_b32 s7, s3
	v_lshl_add_u64 v[2:3], v[2:3], 0, s[6:7]
	v_lshl_add_u64 v[166:167], v[2:3], 0, v[160:161]
	s_add_i32 s7, s88, -2
	s_add_u32 s89, s60, 0x100
	v_mov_b32_e32 v1, v0
	v_ashrrev_i32_e32 v165, 31, v164
	s_addc_u32 s90, s61, 0
	v_lshl_add_u64 v[168:169], s[58:59], 0, v[152:153]
	v_lshl_add_u64 v[170:171], s[58:59], 0, v[154:155]
	s_mov_b32 s64, 0
	s_mov_b64 s[60:61], 0
	s_xor_b64 s[62:63], s[62:63], -1
	v_add_u32_e32 v1, s79, v173
	s_add_i32 s2, s64, 2
	ds_read_b128 v[132:135], v1
	ds_read_b128 v[136:139], v1 offset:1024
	ds_read_b128 v[140:143], v1 offset:2048
	ds_read_b128 v[178:181], v1 offset:3072
	v_add_u32_e32 v1, s80, v173
	s_add_u32 s65, s58, s60
	ds_read_b128 v[182:185], v1
	ds_read_b128 v[188:191], v1 offset:1024
	ds_read_b128 v[192:195], v1 offset:2048
	ds_read_b128 v[196:199], v1 offset:3072
	s_addc_u32 s66, s59, s61
	s_add_u32 s65, s65, 0x100
	s_addc_u32 s66, s66, 0
	s_add_u32 s75, s89, s60
	s_addc_u32 s91, s90, s61
	s_cmp_eq_u32 s7, s64
	s_cselect_b32 s67, s51, s66
	s_cselect_b32 s66, s50, s65
	s_cselect_b32 s65, s53, s91
	s_cselect_b32 s64, s52, s75
	v_lshl_add_u64 v[2:3], v[168:169], 0, s[60:61]
	s_add_i32 m0, s69, 0xc000
	ds_read_b128 v[200:203], v174
	ds_read_b128 v[204:207], v174 offset:1024
	ds_read_b128 v[208:211], v174 offset:2048
	ds_read_b128 v[212:215], v174 offset:3072
	ds_read_b128 v[216:219], v174 offset:4096
	ds_read_b128 v[220:223], v174 offset:5120
	ds_read_b128 v[224:227], v174 offset:6144
	ds_read_b128 v[228:231], v174 offset:7168
	global_load_lds_dwordx4 v[2:3], off
	v_lshl_add_u64 v[2:3], v[170:171], 0, s[60:61]
	s_add_i32 m0, s69, 0xe000
	s_nop 0
	global_load_lds_dwordx4 v[2:3], off
	s_waitcnt vmcnt(8) lgkmcnt(0)
	s_setprio 1
	s_barrier
	v_mfma_f32_16x16x32_bf16 v[128:131], v[132:135], v[200:203], 0
	v_mfma_f32_16x16x32_bf16 v[124:127], v[140:143], v[200:203], 0
	v_mfma_f32_16x16x32_bf16 v[112:115], v[132:135], v[208:211], 0
	v_mfma_f32_16x16x32_bf16 v[108:111], v[140:143], v[208:211], 0
	v_mfma_f32_16x16x32_bf16 v[96:99], v[132:135], v[216:219], 0
	v_mfma_f32_16x16x32_bf16 v[92:95], v[140:143], v[216:219], 0
	v_mfma_f32_16x16x32_bf16 v[80:83], v[132:135], v[224:227], 0
	v_mfma_f32_16x16x32_bf16 v[76:79], v[140:143], v[224:227], 0
	s_setprio 0
	s_setprio 1
	v_mfma_f32_16x16x32_bf16 v[128:131], v[136:139], v[204:207], v[128:131]
	v_mfma_f32_16x16x32_bf16 v[124:127], v[178:181], v[204:207], v[124:127]
	v_mfma_f32_16x16x32_bf16 v[112:115], v[136:139], v[212:215], v[112:115]
	v_mfma_f32_16x16x32_bf16 v[108:111], v[178:181], v[212:215], v[108:111]
	v_mfma_f32_16x16x32_bf16 v[96:99], v[136:139], v[220:223], v[96:99]
	v_mfma_f32_16x16x32_bf16 v[92:95], v[178:181], v[220:223], v[92:95]
	v_mfma_f32_16x16x32_bf16 v[80:83], v[136:139], v[228:231], v[80:83]
	v_mfma_f32_16x16x32_bf16 v[76:79], v[178:181], v[228:231], v[76:79]
	s_setprio 0
	s_setprio 1
	v_mfma_f32_16x16x32_bf16 v[120:123], v[182:185], v[200:203], 0
	v_mfma_f32_16x16x32_bf16 v[116:119], v[192:195], v[200:203], 0
	v_mfma_f32_16x16x32_bf16 v[104:107], v[182:185], v[208:211], 0
	v_mfma_f32_16x16x32_bf16 v[100:103], v[192:195], v[208:211], 0
	v_mfma_f32_16x16x32_bf16 v[88:91], v[182:185], v[216:219], 0
	v_mfma_f32_16x16x32_bf16 v[84:87], v[192:195], v[216:219], 0
	v_mfma_f32_16x16x32_bf16 v[72:75], v[182:185], v[224:227], 0
	v_mfma_f32_16x16x32_bf16 v[68:71], v[192:195], v[224:227], 0
	s_setprio 0
	s_setprio 1
	v_mfma_f32_16x16x32_bf16 v[120:123], v[188:191], v[204:207], v[120:123]
	v_mfma_f32_16x16x32_bf16 v[116:119], v[196:199], v[204:207], v[116:119]
	v_mfma_f32_16x16x32_bf16 v[104:107], v[188:191], v[212:215], v[104:107]
	v_mfma_f32_16x16x32_bf16 v[100:103], v[196:199], v[212:215], v[100:103]
	v_mfma_f32_16x16x32_bf16 v[88:91], v[188:191], v[220:223], v[88:91]
	v_mfma_f32_16x16x32_bf16 v[84:87], v[196:199], v[220:223], v[84:87]
	v_mfma_f32_16x16x32_bf16 v[72:75], v[188:191], v[228:231], v[72:75]
	v_mfma_f32_16x16x32_bf16 v[68:71], v[196:199], v[228:231], v[68:71]
	s_barrier
	s_setprio 0
	s_add_i32 s75, s79, s68
	v_lshl_add_u64 v[232:233], s[64:65], 0, v[148:149]
	s_mov_b32 m0, s75
	ds_read_b128 v[200:203], v174 offset:16384
	ds_read_b128 v[204:207], v174 offset:17408
	ds_read_b128 v[208:211], v174 offset:18432
	ds_read_b128 v[212:215], v174 offset:19456
	ds_read_b128 v[216:219], v174 offset:20480
	ds_read_b128 v[220:223], v174 offset:21504
	ds_read_b128 v[224:227], v174 offset:22528
	ds_read_b128 v[228:231], v174 offset:23552
	global_load_lds_dwordx4 v[232:233], off
	s_add_i32 m0, s75, 0x2000
	s_add_u32 s92, s64, 0xa0000
	v_lshl_add_u64 v[234:235], s[64:65], 0, v[144:145]
	s_addc_u32 s93, s65, 0
	s_add_i32 s75, s80, s68
	global_load_lds_dwordx4 v[234:235], off
	v_lshl_add_u64 v[2:3], s[92:93], 0, v[148:149]
	s_mov_b32 m0, s75
	v_lshl_add_u64 v[236:237], s[66:67], 0, v[150:151]
	global_load_lds_dwordx4 v[2:3], off
	v_lshl_add_u64 v[2:3], s[92:93], 0, v[144:145]
	s_add_i32 m0, s75, 0x2000
	v_lshl_add_u64 v[238:239], s[66:67], 0, v[146:147]
	global_load_lds_dwordx4 v[2:3], off
	s_mov_b32 m0, s69
	s_nop 0
	global_load_lds_dwordx4 v[236:237], off
	s_mov_b32 m0, s70
	s_nop 0
	global_load_lds_dwordx4 v[238:239], off
	s_waitcnt vmcnt(8) lgkmcnt(0)
	s_setprio 1
	s_barrier
	v_mfma_f32_16x16x32_bf16 v[64:67], v[132:135], v[200:203], 0
	v_mfma_f32_16x16x32_bf16 v[60:63], v[140:143], v[200:203], 0
	v_mfma_f32_16x16x32_bf16 v[48:51], v[132:135], v[208:211], 0
	v_mfma_f32_16x16x32_bf16 v[44:47], v[140:143], v[208:211], 0
	v_mfma_f32_16x16x32_bf16 v[32:35], v[132:135], v[216:219], 0
	v_mfma_f32_16x16x32_bf16 v[28:31], v[140:143], v[216:219], 0
	v_mfma_f32_16x16x32_bf16 v[16:19], v[132:135], v[224:227], 0
	v_mfma_f32_16x16x32_bf16 v[12:15], v[140:143], v[224:227], 0
	s_setprio 0
	s_setprio 1
	v_mfma_f32_16x16x32_bf16 v[64:67], v[136:139], v[204:207], v[64:67]
	v_mfma_f32_16x16x32_bf16 v[60:63], v[178:181], v[204:207], v[60:63]
	v_mfma_f32_16x16x32_bf16 v[48:51], v[136:139], v[212:215], v[48:51]
	v_mfma_f32_16x16x32_bf16 v[44:47], v[178:181], v[212:215], v[44:47]
	v_mfma_f32_16x16x32_bf16 v[32:35], v[136:139], v[220:223], v[32:35]
	v_mfma_f32_16x16x32_bf16 v[28:31], v[178:181], v[220:223], v[28:31]
	v_mfma_f32_16x16x32_bf16 v[16:19], v[136:139], v[228:231], v[16:19]
	v_mfma_f32_16x16x32_bf16 v[12:15], v[178:181], v[228:231], v[12:15]
	s_setprio 0
	s_setprio 1
	v_mfma_f32_16x16x32_bf16 v[56:59], v[182:185], v[200:203], 0
	v_mfma_f32_16x16x32_bf16 v[52:55], v[192:195], v[200:203], 0
	v_mfma_f32_16x16x32_bf16 v[40:43], v[182:185], v[208:211], 0
	v_mfma_f32_16x16x32_bf16 v[36:39], v[192:195], v[208:211], 0
	v_mfma_f32_16x16x32_bf16 v[24:27], v[182:185], v[216:219], 0
	v_mfma_f32_16x16x32_bf16 v[20:23], v[192:195], v[216:219], 0
	v_mfma_f32_16x16x32_bf16 v[8:11], v[182:185], v[224:227], 0
	v_mfma_f32_16x16x32_bf16 v[2:5], v[192:195], v[224:227], 0
	s_setprio 0
	s_setprio 1
	v_mfma_f32_16x16x32_bf16 v[56:59], v[188:191], v[204:207], v[56:59]
	v_mfma_f32_16x16x32_bf16 v[52:55], v[196:199], v[204:207], v[52:55]
	v_mfma_f32_16x16x32_bf16 v[40:43], v[188:191], v[212:215], v[40:43]
	v_mfma_f32_16x16x32_bf16 v[36:39], v[196:199], v[212:215], v[36:39]
	v_mfma_f32_16x16x32_bf16 v[24:27], v[188:191], v[220:223], v[24:27]
	v_mfma_f32_16x16x32_bf16 v[20:23], v[196:199], v[220:223], v[20:23]
	v_mfma_f32_16x16x32_bf16 v[8:11], v[188:191], v[228:231], v[8:11]
	v_mfma_f32_16x16x32_bf16 v[2:5], v[196:199], v[228:231], v[2:5]
	s_barrier
	s_setprio 0
	s_branch .Lpeel_mid_p3
	s_nop 0
	s_nop 0
	s_nop 0
	s_nop 0
	s_nop 0
	s_nop 0
	s_nop 0
	s_nop 0

.LBB0_599:
	v_add_u32_e32 v1, s79, v173
	s_add_i32 s2, s64, 2
	ds_read_b128 v[132:135], v1
	ds_read_b128 v[136:139], v1 offset:1024
	ds_read_b128 v[140:143], v1 offset:2048
	ds_read_b128 v[178:181], v1 offset:3072
	v_add_u32_e32 v1, s80, v173
	s_add_u32 s65, s58, s60
	ds_read_b128 v[182:185], v1
	ds_read_b128 v[188:191], v1 offset:1024
	ds_read_b128 v[192:195], v1 offset:2048
	ds_read_b128 v[196:199], v1 offset:3072
	s_addc_u32 s66, s59, s61
	s_add_u32 s65, s65, 0x100
	s_addc_u32 s66, s66, 0
	s_add_u32 s75, s89, s60
	s_addc_u32 s91, s90, s61
	s_cmp_eq_u32 s7, s64
	s_cselect_b32 s67, s51, s66
	s_cselect_b32 s66, s50, s65
	s_cselect_b32 s65, s53, s91
	s_cselect_b32 s64, s52, s75
	v_lshl_add_u64 v[2:3], v[168:169], 0, s[60:61]
	s_add_i32 m0, s69, 0xc000
	ds_read_b128 v[200:203], v174
	ds_read_b128 v[204:207], v174 offset:1024
	ds_read_b128 v[208:211], v174 offset:2048
	ds_read_b128 v[212:215], v174 offset:3072
	ds_read_b128 v[216:219], v174 offset:4096
	ds_read_b128 v[220:223], v174 offset:5120
	ds_read_b128 v[224:227], v174 offset:6144
	ds_read_b128 v[228:231], v174 offset:7168
	global_load_lds_dwordx4 v[2:3], off
	v_lshl_add_u64 v[2:3], v[170:171], 0, s[60:61]
	s_add_i32 m0, s69, 0xe000
	s_nop 0
	global_load_lds_dwordx4 v[2:3], off
	s_waitcnt vmcnt(8) lgkmcnt(0)
	s_setprio 1
	s_barrier
	v_mfma_f32_16x16x32_bf16 v[128:131], v[132:135], v[200:203], v[128:131]
	v_mfma_f32_16x16x32_bf16 v[124:127], v[140:143], v[200:203], v[124:127]
	v_mfma_f32_16x16x32_bf16 v[112:115], v[132:135], v[208:211], v[112:115]
	v_mfma_f32_16x16x32_bf16 v[108:111], v[140:143], v[208:211], v[108:111]
	v_mfma_f32_16x16x32_bf16 v[96:99], v[132:135], v[216:219], v[96:99]
	v_mfma_f32_16x16x32_bf16 v[92:95], v[140:143], v[216:219], v[92:95]
	v_mfma_f32_16x16x32_bf16 v[80:83], v[132:135], v[224:227], v[80:83]
	v_mfma_f32_16x16x32_bf16 v[76:79], v[140:143], v[224:227], v[76:79]
	s_setprio 0
	s_setprio 1
	v_mfma_f32_16x16x32_bf16 v[128:131], v[136:139], v[204:207], v[128:131]
	v_mfma_f32_16x16x32_bf16 v[124:127], v[178:181], v[204:207], v[124:127]
	v_mfma_f32_16x16x32_bf16 v[112:115], v[136:139], v[212:215], v[112:115]
	v_mfma_f32_16x16x32_bf16 v[108:111], v[178:181], v[212:215], v[108:111]
	v_mfma_f32_16x16x32_bf16 v[96:99], v[136:139], v[220:223], v[96:99]
	v_mfma_f32_16x16x32_bf16 v[92:95], v[178:181], v[220:223], v[92:95]
	v_mfma_f32_16x16x32_bf16 v[80:83], v[136:139], v[228:231], v[80:83]
	v_mfma_f32_16x16x32_bf16 v[76:79], v[178:181], v[228:231], v[76:79]
	s_setprio 0
	s_setprio 1
	v_mfma_f32_16x16x32_bf16 v[120:123], v[182:185], v[200:203], v[120:123]
	v_mfma_f32_16x16x32_bf16 v[116:119], v[192:195], v[200:203], v[116:119]
	v_mfma_f32_16x16x32_bf16 v[104:107], v[182:185], v[208:211], v[104:107]
	v_mfma_f32_16x16x32_bf16 v[100:103], v[192:195], v[208:211], v[100:103]
	v_mfma_f32_16x16x32_bf16 v[88:91], v[182:185], v[216:219], v[88:91]
	v_mfma_f32_16x16x32_bf16 v[84:87], v[192:195], v[216:219], v[84:87]
	v_mfma_f32_16x16x32_bf16 v[72:75], v[182:185], v[224:227], v[72:75]
	v_mfma_f32_16x16x32_bf16 v[68:71], v[192:195], v[224:227], v[68:71]
	s_setprio 0
	s_setprio 1
	v_mfma_f32_16x16x32_bf16 v[120:123], v[188:191], v[204:207], v[120:123]
	v_mfma_f32_16x16x32_bf16 v[116:119], v[196:199], v[204:207], v[116:119]
	v_mfma_f32_16x16x32_bf16 v[104:107], v[188:191], v[212:215], v[104:107]
	v_mfma_f32_16x16x32_bf16 v[100:103], v[196:199], v[212:215], v[100:103]
	v_mfma_f32_16x16x32_bf16 v[88:91], v[188:191], v[220:223], v[88:91]
	v_mfma_f32_16x16x32_bf16 v[84:87], v[196:199], v[220:223], v[84:87]
	v_mfma_f32_16x16x32_bf16 v[72:75], v[188:191], v[228:231], v[72:75]
	v_mfma_f32_16x16x32_bf16 v[68:71], v[196:199], v[228:231], v[68:71]
	s_barrier
	s_setprio 0
	s_add_i32 s75, s79, s68
	v_lshl_add_u64 v[232:233], s[64:65], 0, v[148:149]
	s_mov_b32 m0, s75
	ds_read_b128 v[200:203], v174 offset:16384
	ds_read_b128 v[204:207], v174 offset:17408
	ds_read_b128 v[208:211], v174 offset:18432
	ds_read_b128 v[212:215], v174 offset:19456
	ds_read_b128 v[216:219], v174 offset:20480
	ds_read_b128 v[220:223], v174 offset:21504
	ds_read_b128 v[224:227], v174 offset:22528
	ds_read_b128 v[228:231], v174 offset:23552
	global_load_lds_dwordx4 v[232:233], off
	s_add_i32 m0, s75, 0x2000
	s_add_u32 s92, s64, 0xa0000
	v_lshl_add_u64 v[234:235], s[64:65], 0, v[144:145]
	s_addc_u32 s93, s65, 0
	s_add_i32 s75, s80, s68
	global_load_lds_dwordx4 v[234:235], off
	v_lshl_add_u64 v[2:3], s[92:93], 0, v[148:149]
	s_mov_b32 m0, s75
	v_lshl_add_u64 v[236:237], s[66:67], 0, v[150:151]
	global_load_lds_dwordx4 v[2:3], off
	v_lshl_add_u64 v[2:3], s[92:93], 0, v[144:145]
	s_add_i32 m0, s75, 0x2000
	v_lshl_add_u64 v[238:239], s[66:67], 0, v[146:147]
	global_load_lds_dwordx4 v[2:3], off
	s_mov_b32 m0, s69
	s_nop 0
	global_load_lds_dwordx4 v[236:237], off
	s_mov_b32 m0, s70
	s_nop 0
	global_load_lds_dwordx4 v[238:239], off
	s_waitcnt vmcnt(8) lgkmcnt(0)
	s_setprio 1
	s_barrier
	v_mfma_f32_16x16x32_bf16 v[64:67], v[132:135], v[200:203], v[64:67]
	v_mfma_f32_16x16x32_bf16 v[60:63], v[140:143], v[200:203], v[60:63]
	v_mfma_f32_16x16x32_bf16 v[48:51], v[132:135], v[208:211], v[48:51]
	v_mfma_f32_16x16x32_bf16 v[44:47], v[140:143], v[208:211], v[44:47]
	v_mfma_f32_16x16x32_bf16 v[32:35], v[132:135], v[216:219], v[32:35]
	v_mfma_f32_16x16x32_bf16 v[28:31], v[140:143], v[216:219], v[28:31]
	v_mfma_f32_16x16x32_bf16 v[16:19], v[132:135], v[224:227], v[16:19]
	v_mfma_f32_16x16x32_bf16 v[12:15], v[140:143], v[224:227], v[12:15]
	s_setprio 0
	s_setprio 1
	v_mfma_f32_16x16x32_bf16 v[64:67], v[136:139], v[204:207], v[64:67]
	v_mfma_f32_16x16x32_bf16 v[60:63], v[178:181], v[204:207], v[60:63]
	v_mfma_f32_16x16x32_bf16 v[48:51], v[136:139], v[212:215], v[48:51]
	v_mfma_f32_16x16x32_bf16 v[44:47], v[178:181], v[212:215], v[44:47]
	v_mfma_f32_16x16x32_bf16 v[32:35], v[136:139], v[220:223], v[32:35]
	v_mfma_f32_16x16x32_bf16 v[28:31], v[178:181], v[220:223], v[28:31]
	v_mfma_f32_16x16x32_bf16 v[16:19], v[136:139], v[228:231], v[16:19]
	v_mfma_f32_16x16x32_bf16 v[12:15], v[178:181], v[228:231], v[12:15]
	s_setprio 0
	s_setprio 1
	v_mfma_f32_16x16x32_bf16 v[56:59], v[182:185], v[200:203], v[56:59]
	v_mfma_f32_16x16x32_bf16 v[52:55], v[192:195], v[200:203], v[52:55]
	v_mfma_f32_16x16x32_bf16 v[40:43], v[182:185], v[208:211], v[40:43]
	v_mfma_f32_16x16x32_bf16 v[36:39], v[192:195], v[208:211], v[36:39]
	v_mfma_f32_16x16x32_bf16 v[24:27], v[182:185], v[216:219], v[24:27]
	v_mfma_f32_16x16x32_bf16 v[20:23], v[192:195], v[216:219], v[20:23]
	v_mfma_f32_16x16x32_bf16 v[8:11], v[182:185], v[224:227], v[8:11]
	v_mfma_f32_16x16x32_bf16 v[2:5], v[192:195], v[224:227], v[4:7]
	s_setprio 0
	s_setprio 1
	v_mfma_f32_16x16x32_bf16 v[56:59], v[188:191], v[204:207], v[56:59]
	v_mfma_f32_16x16x32_bf16 v[52:55], v[196:199], v[204:207], v[52:55]
	v_mfma_f32_16x16x32_bf16 v[40:43], v[188:191], v[212:215], v[40:43]
	v_mfma_f32_16x16x32_bf16 v[36:39], v[196:199], v[212:215], v[36:39]
	v_mfma_f32_16x16x32_bf16 v[24:27], v[188:191], v[220:223], v[24:27]
	v_mfma_f32_16x16x32_bf16 v[20:23], v[196:199], v[220:223], v[20:23]
	v_mfma_f32_16x16x32_bf16 v[8:11], v[188:191], v[228:231], v[8:11]
	v_mfma_f32_16x16x32_bf16 v[2:5], v[196:199], v[228:231], v[2:5]
	s_barrier
	s_setprio 0
.Lpeel_mid_p3:
	s_add_i32 s75, 0, 0x18000
	v_add_u32_e32 v1, s75, v173
	s_add_i32 s91, 0, 0x1c000
	ds_read_b128 v[132:135], v1
	ds_read_b128 v[136:139], v1 offset:1024
	ds_read_b128 v[140:143], v1 offset:2048
	ds_read_b128 v[178:181], v1 offset:3072
	v_add_u32_e32 v1, s91, v173
	ds_read_b128 v[182:185], v1
	ds_read_b128 v[188:191], v1 offset:1024
	ds_read_b128 v[192:195], v1 offset:2048
	ds_read_b128 v[196:199], v1 offset:3072
	s_add_u32 s66, s66, 0xa0000
	s_addc_u32 s67, s67, 0
	s_mov_b32 m0, s71
	v_lshl_add_u64 v[6:7], s[66:67], 0, v[150:151]
	ds_read_b128 v[200:203], v174 offset:32768
	ds_read_b128 v[204:207], v174 offset:33792
	ds_read_b128 v[208:211], v174 offset:34816
	ds_read_b128 v[212:215], v174 offset:35840
	ds_read_b128 v[216:219], v174 offset:36864
	ds_read_b128 v[220:223], v174 offset:37888
	ds_read_b128 v[224:227], v174 offset:38912
	ds_read_b128 v[228:231], v174 offset:39936
	global_load_lds_dwordx4 v[6:7], off
	v_lshl_add_u64 v[6:7], s[66:67], 0, v[146:147]
	s_mov_b32 m0, s72
	s_nop 0
	global_load_lds_dwordx4 v[6:7], off
	s_waitcnt vmcnt(8) lgkmcnt(0)
	s_setprio 1
	s_barrier
	v_mfma_f32_16x16x32_bf16 v[128:131], v[132:135], v[200:203], v[128:131]
	v_mfma_f32_16x16x32_bf16 v[124:127], v[140:143], v[200:203], v[124:127]
	v_mfma_f32_16x16x32_bf16 v[112:115], v[132:135], v[208:211], v[112:115]
	v_mfma_f32_16x16x32_bf16 v[108:111], v[140:143], v[208:211], v[108:111]
	v_mfma_f32_16x16x32_bf16 v[96:99], v[132:135], v[216:219], v[96:99]
	v_mfma_f32_16x16x32_bf16 v[92:95], v[140:143], v[216:219], v[92:95]
	v_mfma_f32_16x16x32_bf16 v[80:83], v[132:135], v[224:227], v[80:83]
	v_mfma_f32_16x16x32_bf16 v[76:79], v[140:143], v[224:227], v[76:79]
	s_setprio 0
	s_setprio 1
	v_mfma_f32_16x16x32_bf16 v[128:131], v[136:139], v[204:207], v[128:131]
	v_mfma_f32_16x16x32_bf16 v[124:127], v[178:181], v[204:207], v[124:127]
	v_mfma_f32_16x16x32_bf16 v[112:115], v[136:139], v[212:215], v[112:115]
	v_mfma_f32_16x16x32_bf16 v[108:111], v[178:181], v[212:215], v[108:111]
	v_mfma_f32_16x16x32_bf16 v[96:99], v[136:139], v[220:223], v[96:99]
	v_mfma_f32_16x16x32_bf16 v[92:95], v[178:181], v[220:223], v[92:95]
	v_mfma_f32_16x16x32_bf16 v[80:83], v[136:139], v[228:231], v[80:83]
	v_mfma_f32_16x16x32_bf16 v[76:79], v[178:181], v[228:231], v[76:79]
	s_setprio 0
	s_setprio 1
	v_mfma_f32_16x16x32_bf16 v[120:123], v[182:185], v[200:203], v[120:123]
	v_mfma_f32_16x16x32_bf16 v[116:119], v[192:195], v[200:203], v[116:119]
	v_mfma_f32_16x16x32_bf16 v[104:107], v[182:185], v[208:211], v[104:107]
	v_mfma_f32_16x16x32_bf16 v[100:103], v[192:195], v[208:211], v[100:103]
	v_mfma_f32_16x16x32_bf16 v[88:91], v[182:185], v[216:219], v[88:91]
	v_mfma_f32_16x16x32_bf16 v[84:87], v[192:195], v[216:219], v[84:87]
	v_mfma_f32_16x16x32_bf16 v[72:75], v[182:185], v[224:227], v[72:75]
	v_mfma_f32_16x16x32_bf16 v[68:71], v[192:195], v[224:227], v[68:71]
	s_setprio 0
	s_setprio 1
	v_mfma_f32_16x16x32_bf16 v[120:123], v[188:191], v[204:207], v[120:123]
	v_mfma_f32_16x16x32_bf16 v[116:119], v[196:199], v[204:207], v[116:119]
	v_mfma_f32_16x16x32_bf16 v[104:107], v[188:191], v[212:215], v[104:107]
	v_mfma_f32_16x16x32_bf16 v[100:103], v[196:199], v[212:215], v[100:103]
	v_mfma_f32_16x16x32_bf16 v[88:91], v[188:191], v[220:223], v[88:91]
	v_mfma_f32_16x16x32_bf16 v[84:87], v[196:199], v[220:223], v[84:87]
	v_mfma_f32_16x16x32_bf16 v[72:75], v[188:191], v[228:231], v[72:75]
	v_mfma_f32_16x16x32_bf16 v[68:71], v[196:199], v[228:231], v[68:71]
	s_barrier
	s_setprio 0
	s_add_i32 s66, s75, s68
	v_lshl_add_u64 v[6:7], v[232:233], 0, s[14:15]
	s_mov_b32 m0, s66
	ds_read_b128 v[200:203], v174 offset:49152
	ds_read_b128 v[204:207], v174 offset:50176
	ds_read_b128 v[208:211], v174 offset:51200
	ds_read_b128 v[212:215], v174 offset:52224
	ds_read_b128 v[216:219], v174 offset:53248
	ds_read_b128 v[220:223], v174 offset:54272
	ds_read_b128 v[224:227], v174 offset:55296
	ds_read_b128 v[228:231], v174 offset:56320
	global_load_lds_dwordx4 v[6:7], off
	s_add_i32 m0, s66, 0x2000
	s_add_u32 s64, s64, 0xa0080
	v_lshl_add_u64 v[6:7], v[234:235], 0, s[14:15]
	s_addc_u32 s65, s65, 0
	s_add_i32 s66, s91, s68
	global_load_lds_dwordx4 v[6:7], off
	v_lshl_add_u64 v[6:7], s[64:65], 0, v[148:149]
	s_mov_b32 m0, s66
	s_nop 0
	global_load_lds_dwordx4 v[6:7], off
	v_lshl_add_u64 v[6:7], s[64:65], 0, v[144:145]
	s_add_i32 m0, s66, 0x2000
	s_nop 0
	global_load_lds_dwordx4 v[6:7], off
	v_lshl_add_u64 v[6:7], v[236:237], 0, s[14:15]
	s_mov_b32 m0, s73
	s_nop 0
	global_load_lds_dwordx4 v[6:7], off
	v_lshl_add_u64 v[6:7], v[238:239], 0, s[14:15]
	s_mov_b32 m0, s76
	s_nop 0
	global_load_lds_dwordx4 v[6:7], off
	s_waitcnt vmcnt(8) lgkmcnt(0)
	s_setprio 1
	s_barrier
	v_mfma_f32_16x16x32_bf16 v[64:67], v[132:135], v[200:203], v[64:67]
	v_mfma_f32_16x16x32_bf16 v[60:63], v[140:143], v[200:203], v[60:63]
	v_mfma_f32_16x16x32_bf16 v[48:51], v[132:135], v[208:211], v[48:51]
	v_mfma_f32_16x16x32_bf16 v[44:47], v[140:143], v[208:211], v[44:47]
	v_mfma_f32_16x16x32_bf16 v[32:35], v[132:135], v[216:219], v[32:35]
	v_mfma_f32_16x16x32_bf16 v[28:31], v[140:143], v[216:219], v[28:31]
	v_mfma_f32_16x16x32_bf16 v[16:19], v[132:135], v[224:227], v[16:19]
	v_mfma_f32_16x16x32_bf16 v[12:15], v[140:143], v[224:227], v[12:15]
	s_setprio 0
	s_setprio 1
	v_mfma_f32_16x16x32_bf16 v[64:67], v[136:139], v[204:207], v[64:67]
	v_mfma_f32_16x16x32_bf16 v[60:63], v[178:181], v[204:207], v[60:63]
	v_mfma_f32_16x16x32_bf16 v[48:51], v[136:139], v[212:215], v[48:51]
	s_add_u32 s60, s60, 0x100
	v_mfma_f32_16x16x32_bf16 v[44:47], v[178:181], v[212:215], v[44:47]
	s_addc_u32 s61, s61, 0
	v_mfma_f32_16x16x32_bf16 v[32:35], v[136:139], v[220:223], v[32:35]
	s_cmp_eq_u32 s2, 16
	v_mfma_f32_16x16x32_bf16 v[28:31], v[178:181], v[220:223], v[28:31]
	s_cselect_b32 s100, 1, 0
	v_mfma_f32_16x16x32_bf16 v[16:19], v[136:139], v[228:231], v[16:19]
	s_cmp_eq_u32 s2, 24
	v_mfma_f32_16x16x32_bf16 v[12:15], v[178:181], v[228:231], v[12:15]
	s_cselect_b32 s101, 1, 0
	s_setprio 0
	s_setprio 1
	v_mfma_f32_16x16x32_bf16 v[56:59], v[182:185], v[200:203], v[56:59]
	s_or_b32 s100, s100, s101
	v_mfma_f32_16x16x32_bf16 v[52:55], v[192:195], v[200:203], v[52:55]
	s_cmp_eq_u64 s[62:63], 0
	v_mfma_f32_16x16x32_bf16 v[40:43], v[182:185], v[208:211], v[40:43]
	s_cselect_b32 s100, s100, 0
	v_mfma_f32_16x16x32_bf16 v[36:39], v[192:195], v[208:211], v[36:39]
	s_cmp_ge_i32 s2, s88
	v_mfma_f32_16x16x32_bf16 v[24:27], v[182:185], v[216:219], v[24:27]
	s_cselect_b32 s67, 1, 0
	v_mfma_f32_16x16x32_bf16 v[20:23], v[192:195], v[216:219], v[20:23]
	s_cmp_eq_u64 s[18:19], 0
	v_mfma_f32_16x16x32_bf16 v[6:9], v[182:185], v[224:227], v[8:11]
	s_cselect_b32 s66, 0, s100
	v_mfma_f32_16x16x32_bf16 v[2:5], v[192:195], v[224:227], v[2:5]
	s_setprio 0
	s_setprio 1
	s_cselect_b32 s100, s100, 0
	v_mfma_f32_16x16x32_bf16 v[56:59], v[188:191], v[204:207], v[56:59]
	s_or_b32 s66, s66, s67
	v_mfma_f32_16x16x32_bf16 v[52:55], v[196:199], v[204:207], v[52:55]
	s_mov_b32 s64, s2
	v_mfma_f32_16x16x32_bf16 v[40:43], v[188:191], v[212:215], v[40:43]
	s_cmp_lg_u32 s100, 0
	v_mfma_f32_16x16x32_bf16 v[36:39], v[196:199], v[212:215], v[36:39]
	v_mfma_f32_16x16x32_bf16 v[24:27], v[188:191], v[220:223], v[24:27]
	v_mfma_f32_16x16x32_bf16 v[20:23], v[196:199], v[220:223], v[20:23]
	v_mfma_f32_16x16x32_bf16 v[8:11], v[188:191], v[228:231], v[6:9]
	v_mfma_f32_16x16x32_bf16 v[4:7], v[196:199], v[228:231], v[2:5]
	s_setprio 0
	s_cbranch_scc0 .Lhk_skipB

.LBB0_671:
	s_add_u32 s6, s6, 0x80080
	s_addc_u32 s7, s7, 0
	s_add_u32 s5, s40, 0x100
	s_addc_u32 s25, s41, 0
	s_mov_b32 s56, -2
	ds_read_b128 v[128:131], v185
	ds_read_b128 v[132:135], v185 offset:1024
	ds_read_b128 v[136:139], v185 offset:2048
	ds_read_b128 v[140:143], v185 offset:3072
	ds_read_b128 v[162:165], v186
	ds_read_b128 v[166:169], v186 offset:1024
	ds_read_b128 v[170:173], v186 offset:2048
	ds_read_b128 v[174:177], v186 offset:3072
	s_add_u32 s38, s6, 0xfff80080
	s_addc_u32 s39, s7, -1
	s_cmp_eq_u32 s56, 28
	s_cselect_b32 s41, s27, s39
	s_cselect_b32 s40, s26, s38
	s_cselect_b32 s39, s23, s25
	s_cselect_b32 s38, s22, s5
	v_lshl_add_u64 v[182:183], s[6:7], 0, v[158:159]
	s_add_i32 m0, s42, 0xc000
	ds_read_b128 v[178:181], v188
	ds_read_b128 v[192:195], v188 offset:1024
	ds_read_b128 v[196:199], v188 offset:2048
	ds_read_b128 v[200:203], v188 offset:3072
	ds_read_b128 v[204:207], v188 offset:4096
	ds_read_b128 v[208:211], v188 offset:5120
	ds_read_b128 v[212:215], v188 offset:6144
	ds_read_b128 v[216:219], v188 offset:7168
	global_load_lds_dwordx4 v[182:183], off
	v_lshl_add_u64 v[182:183], s[6:7], 0, v[160:161]
	s_add_i32 m0, s42, 0xe000
	s_nop 0
	global_load_lds_dwordx4 v[182:183], off
	s_waitcnt vmcnt(8) lgkmcnt(0)
	s_setprio 1
	s_barrier
	v_mfma_f32_16x16x32_bf16 v[124:127], v[128:131], v[178:181], 0
	v_mfma_f32_16x16x32_bf16 v[120:123], v[136:139], v[178:181], 0
	v_mfma_f32_16x16x32_bf16 v[108:111], v[128:131], v[196:199], 0
	v_mfma_f32_16x16x32_bf16 v[104:107], v[136:139], v[196:199], 0
	v_mfma_f32_16x16x32_bf16 v[92:95], v[128:131], v[204:207], 0
	v_mfma_f32_16x16x32_bf16 v[88:91], v[136:139], v[204:207], 0
	v_mfma_f32_16x16x32_bf16 v[76:79], v[128:131], v[212:215], 0
	v_mfma_f32_16x16x32_bf16 v[72:75], v[136:139], v[212:215], 0
	s_setprio 0
	s_setprio 1
	v_mfma_f32_16x16x32_bf16 v[124:127], v[132:135], v[192:195], v[124:127]
	v_mfma_f32_16x16x32_bf16 v[120:123], v[140:143], v[192:195], v[120:123]
	v_mfma_f32_16x16x32_bf16 v[108:111], v[132:135], v[200:203], v[108:111]
	v_mfma_f32_16x16x32_bf16 v[104:107], v[140:143], v[200:203], v[104:107]
	v_mfma_f32_16x16x32_bf16 v[92:95], v[132:135], v[208:211], v[92:95]
	v_mfma_f32_16x16x32_bf16 v[88:91], v[140:143], v[208:211], v[88:91]
	v_mfma_f32_16x16x32_bf16 v[76:79], v[132:135], v[216:219], v[76:79]
	v_mfma_f32_16x16x32_bf16 v[72:75], v[140:143], v[216:219], v[72:75]
	s_setprio 0
	s_setprio 1
	v_mfma_f32_16x16x32_bf16 v[116:119], v[162:165], v[178:181], 0
	v_mfma_f32_16x16x32_bf16 v[112:115], v[170:173], v[178:181], 0
	v_mfma_f32_16x16x32_bf16 v[100:103], v[162:165], v[196:199], 0
	v_mfma_f32_16x16x32_bf16 v[96:99], v[170:173], v[196:199], 0
	v_mfma_f32_16x16x32_bf16 v[84:87], v[162:165], v[204:207], 0
	v_mfma_f32_16x16x32_bf16 v[80:83], v[170:173], v[204:207], 0
	v_mfma_f32_16x16x32_bf16 v[68:71], v[162:165], v[212:215], 0
	v_mfma_f32_16x16x32_bf16 v[64:67], v[170:173], v[212:215], 0
	s_setprio 0
	s_setprio 1
	v_mfma_f32_16x16x32_bf16 v[116:119], v[166:169], v[192:195], v[116:119]
	v_mfma_f32_16x16x32_bf16 v[112:115], v[174:177], v[192:195], v[112:115]
	v_mfma_f32_16x16x32_bf16 v[100:103], v[166:169], v[200:203], v[100:103]
	v_mfma_f32_16x16x32_bf16 v[96:99], v[174:177], v[200:203], v[96:99]
	v_mfma_f32_16x16x32_bf16 v[84:87], v[166:169], v[208:211], v[84:87]
	v_mfma_f32_16x16x32_bf16 v[80:83], v[174:177], v[208:211], v[80:83]
	v_mfma_f32_16x16x32_bf16 v[68:71], v[166:169], v[216:219], v[68:71]
	v_mfma_f32_16x16x32_bf16 v[64:67], v[174:177], v[216:219], v[64:67]
	s_barrier
	s_setprio 0
	s_add_i32 s57, s51, s35
	v_lshl_add_u64 v[182:183], s[38:39], 0, v[148:149]
	s_mov_b32 m0, s57
	ds_read_b128 v[178:181], v188 offset:16384
	ds_read_b128 v[192:195], v188 offset:17408
	ds_read_b128 v[196:199], v188 offset:18432
	ds_read_b128 v[200:203], v188 offset:19456
	ds_read_b128 v[204:207], v188 offset:20480
	ds_read_b128 v[208:211], v188 offset:21504
	ds_read_b128 v[212:215], v188 offset:22528
	ds_read_b128 v[216:219], v188 offset:23552
	global_load_lds_dwordx4 v[182:183], off
	s_add_i32 m0, s57, 0x2000
	s_add_u32 s58, s38, 0x80000
	v_lshl_add_u64 v[220:221], s[38:39], 0, v[144:145]
	s_addc_u32 s59, s39, 0
	s_add_i32 s57, s52, s35
	global_load_lds_dwordx4 v[220:221], off
	v_lshl_add_u64 v[222:223], s[58:59], 0, v[148:149]
	s_mov_b32 m0, s57
	v_lshl_add_u64 v[224:225], s[40:41], 0, v[146:147]
	global_load_lds_dwordx4 v[222:223], off
	v_lshl_add_u64 v[222:223], s[58:59], 0, v[144:145]
	s_add_i32 m0, s57, 0x2000
	s_nop 0
	global_load_lds_dwordx4 v[222:223], off
	v_lshl_add_u64 v[222:223], s[40:41], 0, v[150:151]
	s_mov_b32 m0, s42
	s_nop 0
	global_load_lds_dwordx4 v[222:223], off
	s_mov_b32 m0, s43
	s_nop 0
	global_load_lds_dwordx4 v[224:225], off
	s_waitcnt vmcnt(8) lgkmcnt(0)
	s_setprio 1
	s_barrier
	v_mfma_f32_16x16x32_bf16 v[60:63], v[128:131], v[178:181], 0
	v_mfma_f32_16x16x32_bf16 v[56:59], v[136:139], v[178:181], 0
	v_mfma_f32_16x16x32_bf16 v[44:47], v[128:131], v[196:199], 0
	v_mfma_f32_16x16x32_bf16 v[40:43], v[136:139], v[196:199], 0
	v_mfma_f32_16x16x32_bf16 v[28:31], v[128:131], v[204:207], 0
	v_mfma_f32_16x16x32_bf16 v[24:27], v[136:139], v[204:207], 0
	v_mfma_f32_16x16x32_bf16 v[12:15], v[128:131], v[212:215], 0
	v_mfma_f32_16x16x32_bf16 v[8:11], v[136:139], v[212:215], 0
	s_setprio 0
	s_setprio 1
	v_mfma_f32_16x16x32_bf16 v[60:63], v[132:135], v[192:195], v[60:63]
	v_mfma_f32_16x16x32_bf16 v[56:59], v[140:143], v[192:195], v[56:59]
	v_mfma_f32_16x16x32_bf16 v[44:47], v[132:135], v[200:203], v[44:47]
	v_mfma_f32_16x16x32_bf16 v[40:43], v[140:143], v[200:203], v[40:43]
	v_mfma_f32_16x16x32_bf16 v[28:31], v[132:135], v[208:211], v[28:31]
	v_mfma_f32_16x16x32_bf16 v[24:27], v[140:143], v[208:211], v[24:27]
	v_mfma_f32_16x16x32_bf16 v[12:15], v[132:135], v[216:219], v[12:15]
	v_mfma_f32_16x16x32_bf16 v[8:11], v[140:143], v[216:219], v[8:11]
	s_setprio 0
	s_setprio 1
	v_mfma_f32_16x16x32_bf16 v[52:55], v[162:165], v[178:181], 0
	v_mfma_f32_16x16x32_bf16 v[48:51], v[170:173], v[178:181], 0
	v_mfma_f32_16x16x32_bf16 v[36:39], v[162:165], v[196:199], 0
	v_mfma_f32_16x16x32_bf16 v[32:35], v[170:173], v[196:199], 0
	v_mfma_f32_16x16x32_bf16 v[20:23], v[162:165], v[204:207], 0
	v_mfma_f32_16x16x32_bf16 v[16:19], v[170:173], v[204:207], 0
	v_mfma_f32_16x16x32_bf16 v[4:7], v[162:165], v[212:215], 0
	v_mfma_f32_16x16x32_bf16 v[0:3], v[170:173], v[212:215], 0
	s_setprio 0
	s_setprio 1
	v_mfma_f32_16x16x32_bf16 v[52:55], v[166:169], v[192:195], v[52:55]
	v_mfma_f32_16x16x32_bf16 v[48:51], v[174:177], v[192:195], v[48:51]
	v_mfma_f32_16x16x32_bf16 v[36:39], v[166:169], v[200:203], v[36:39]
	v_mfma_f32_16x16x32_bf16 v[32:35], v[174:177], v[200:203], v[32:35]
	v_mfma_f32_16x16x32_bf16 v[20:23], v[166:169], v[208:211], v[20:23]
	v_mfma_f32_16x16x32_bf16 v[16:19], v[174:177], v[208:211], v[16:19]
	v_mfma_f32_16x16x32_bf16 v[4:7], v[166:169], v[216:219], v[4:7]
	v_mfma_f32_16x16x32_bf16 v[0:3], v[174:177], v[216:219], v[0:3]
	s_barrier
	s_setprio 0
	s_branch .Lpeel_mid_p4
	s_nop 0
	s_nop 0
	s_nop 0
	s_nop 0
	s_nop 0
	s_nop 0
	s_nop 0
	s_nop 0
	s_nop 0
	s_nop 0
.LBB0_672:
	ds_read_b128 v[128:131], v185
	ds_read_b128 v[132:135], v185 offset:1024
	ds_read_b128 v[136:139], v185 offset:2048
	ds_read_b128 v[140:143], v185 offset:3072
	ds_read_b128 v[162:165], v186
	ds_read_b128 v[166:169], v186 offset:1024
	ds_read_b128 v[170:173], v186 offset:2048
	ds_read_b128 v[174:177], v186 offset:3072
	s_add_u32 s38, s6, 0xfff80080
	s_addc_u32 s39, s7, -1
	s_cmp_eq_u32 s56, 28
	s_cselect_b32 s41, s27, s39
	s_cselect_b32 s40, s26, s38
	s_cselect_b32 s39, s23, s25
	s_cselect_b32 s38, s22, s5
	v_lshl_add_u64 v[182:183], s[6:7], 0, v[158:159]
	s_add_i32 m0, s42, 0xc000
	ds_read_b128 v[178:181], v188
	ds_read_b128 v[192:195], v188 offset:1024
	ds_read_b128 v[196:199], v188 offset:2048
	ds_read_b128 v[200:203], v188 offset:3072
	ds_read_b128 v[204:207], v188 offset:4096
	ds_read_b128 v[208:211], v188 offset:5120
	ds_read_b128 v[212:215], v188 offset:6144
	ds_read_b128 v[216:219], v188 offset:7168
	global_load_lds_dwordx4 v[182:183], off
	v_lshl_add_u64 v[182:183], s[6:7], 0, v[160:161]
	s_add_i32 m0, s42, 0xe000
	s_nop 0
	global_load_lds_dwordx4 v[182:183], off
	s_waitcnt vmcnt(8) lgkmcnt(0)
	s_setprio 1
	s_barrier
	v_mfma_f32_16x16x32_bf16 v[124:127], v[128:131], v[178:181], v[124:127]
	v_mfma_f32_16x16x32_bf16 v[120:123], v[136:139], v[178:181], v[120:123]
	v_mfma_f32_16x16x32_bf16 v[108:111], v[128:131], v[196:199], v[108:111]
	v_mfma_f32_16x16x32_bf16 v[104:107], v[136:139], v[196:199], v[104:107]
	v_mfma_f32_16x16x32_bf16 v[92:95], v[128:131], v[204:207], v[92:95]
	v_mfma_f32_16x16x32_bf16 v[88:91], v[136:139], v[204:207], v[88:91]
	v_mfma_f32_16x16x32_bf16 v[76:79], v[128:131], v[212:215], v[76:79]
	v_mfma_f32_16x16x32_bf16 v[72:75], v[136:139], v[212:215], v[72:75]
	s_setprio 0
	s_setprio 1
	v_mfma_f32_16x16x32_bf16 v[124:127], v[132:135], v[192:195], v[124:127]
	v_mfma_f32_16x16x32_bf16 v[120:123], v[140:143], v[192:195], v[120:123]
	v_mfma_f32_16x16x32_bf16 v[108:111], v[132:135], v[200:203], v[108:111]
	v_mfma_f32_16x16x32_bf16 v[104:107], v[140:143], v[200:203], v[104:107]
	v_mfma_f32_16x16x32_bf16 v[92:95], v[132:135], v[208:211], v[92:95]
	v_mfma_f32_16x16x32_bf16 v[88:91], v[140:143], v[208:211], v[88:91]
	v_mfma_f32_16x16x32_bf16 v[76:79], v[132:135], v[216:219], v[76:79]
	v_mfma_f32_16x16x32_bf16 v[72:75], v[140:143], v[216:219], v[72:75]
	s_setprio 0
	s_setprio 1
	v_mfma_f32_16x16x32_bf16 v[116:119], v[162:165], v[178:181], v[116:119]
	v_mfma_f32_16x16x32_bf16 v[112:115], v[170:173], v[178:181], v[112:115]
	v_mfma_f32_16x16x32_bf16 v[100:103], v[162:165], v[196:199], v[100:103]
	v_mfma_f32_16x16x32_bf16 v[96:99], v[170:173], v[196:199], v[96:99]
	v_mfma_f32_16x16x32_bf16 v[84:87], v[162:165], v[204:207], v[84:87]
	v_mfma_f32_16x16x32_bf16 v[80:83], v[170:173], v[204:207], v[80:83]
	v_mfma_f32_16x16x32_bf16 v[68:71], v[162:165], v[212:215], v[68:71]
	v_mfma_f32_16x16x32_bf16 v[64:67], v[170:173], v[212:215], v[64:67]
	s_setprio 0
	s_setprio 1
	v_mfma_f32_16x16x32_bf16 v[116:119], v[166:169], v[192:195], v[116:119]
	v_mfma_f32_16x16x32_bf16 v[112:115], v[174:177], v[192:195], v[112:115]
	v_mfma_f32_16x16x32_bf16 v[100:103], v[166:169], v[200:203], v[100:103]
	v_mfma_f32_16x16x32_bf16 v[96:99], v[174:177], v[200:203], v[96:99]
	v_mfma_f32_16x16x32_bf16 v[84:87], v[166:169], v[208:211], v[84:87]
	v_mfma_f32_16x16x32_bf16 v[80:83], v[174:177], v[208:211], v[80:83]
	v_mfma_f32_16x16x32_bf16 v[68:71], v[166:169], v[216:219], v[68:71]
	v_mfma_f32_16x16x32_bf16 v[64:67], v[174:177], v[216:219], v[64:67]
	s_barrier
	s_setprio 0
	s_add_i32 s57, s51, s35
	v_lshl_add_u64 v[182:183], s[38:39], 0, v[148:149]
	s_mov_b32 m0, s57
	ds_read_b128 v[178:181], v188 offset:16384
	ds_read_b128 v[192:195], v188 offset:17408
	ds_read_b128 v[196:199], v188 offset:18432
	ds_read_b128 v[200:203], v188 offset:19456
	ds_read_b128 v[204:207], v188 offset:20480
	ds_read_b128 v[208:211], v188 offset:21504
	ds_read_b128 v[212:215], v188 offset:22528
	ds_read_b128 v[216:219], v188 offset:23552
	global_load_lds_dwordx4 v[182:183], off
	s_add_i32 m0, s57, 0x2000
	s_add_u32 s58, s38, 0x80000
	v_lshl_add_u64 v[220:221], s[38:39], 0, v[144:145]
	s_addc_u32 s59, s39, 0
	s_add_i32 s57, s52, s35
	global_load_lds_dwordx4 v[220:221], off
	v_lshl_add_u64 v[222:223], s[58:59], 0, v[148:149]
	s_mov_b32 m0, s57
	v_lshl_add_u64 v[224:225], s[40:41], 0, v[146:147]
	global_load_lds_dwordx4 v[222:223], off
	v_lshl_add_u64 v[222:223], s[58:59], 0, v[144:145]
	s_add_i32 m0, s57, 0x2000
	s_nop 0
	global_load_lds_dwordx4 v[222:223], off
	v_lshl_add_u64 v[222:223], s[40:41], 0, v[150:151]
	s_mov_b32 m0, s42
	s_nop 0
	global_load_lds_dwordx4 v[222:223], off
	s_mov_b32 m0, s43
	s_nop 0
	global_load_lds_dwordx4 v[224:225], off
	s_waitcnt vmcnt(8) lgkmcnt(0)
	s_setprio 1
	s_barrier
	v_mfma_f32_16x16x32_bf16 v[60:63], v[128:131], v[178:181], v[60:63]
	v_mfma_f32_16x16x32_bf16 v[56:59], v[136:139], v[178:181], v[56:59]
	v_mfma_f32_16x16x32_bf16 v[44:47], v[128:131], v[196:199], v[44:47]
	v_mfma_f32_16x16x32_bf16 v[40:43], v[136:139], v[196:199], v[40:43]
	v_mfma_f32_16x16x32_bf16 v[28:31], v[128:131], v[204:207], v[28:31]
	v_mfma_f32_16x16x32_bf16 v[24:27], v[136:139], v[204:207], v[24:27]
	v_mfma_f32_16x16x32_bf16 v[12:15], v[128:131], v[212:215], v[12:15]
	v_mfma_f32_16x16x32_bf16 v[8:11], v[136:139], v[212:215], v[8:11]
	s_setprio 0
	s_setprio 1
	v_mfma_f32_16x16x32_bf16 v[60:63], v[132:135], v[192:195], v[60:63]
	v_mfma_f32_16x16x32_bf16 v[56:59], v[140:143], v[192:195], v[56:59]
	v_mfma_f32_16x16x32_bf16 v[44:47], v[132:135], v[200:203], v[44:47]
	v_mfma_f32_16x16x32_bf16 v[40:43], v[140:143], v[200:203], v[40:43]
	v_mfma_f32_16x16x32_bf16 v[28:31], v[132:135], v[208:211], v[28:31]
	v_mfma_f32_16x16x32_bf16 v[24:27], v[140:143], v[208:211], v[24:27]
	v_mfma_f32_16x16x32_bf16 v[12:15], v[132:135], v[216:219], v[12:15]
	v_mfma_f32_16x16x32_bf16 v[8:11], v[140:143], v[216:219], v[8:11]
	s_setprio 0
	s_setprio 1
	v_mfma_f32_16x16x32_bf16 v[52:55], v[162:165], v[178:181], v[52:55]
	v_mfma_f32_16x16x32_bf16 v[48:51], v[170:173], v[178:181], v[48:51]
	v_mfma_f32_16x16x32_bf16 v[36:39], v[162:165], v[196:199], v[36:39]
	v_mfma_f32_16x16x32_bf16 v[32:35], v[170:173], v[196:199], v[32:35]
	v_mfma_f32_16x16x32_bf16 v[20:23], v[162:165], v[204:207], v[20:23]
	v_mfma_f32_16x16x32_bf16 v[16:19], v[170:173], v[204:207], v[16:19]
	v_mfma_f32_16x16x32_bf16 v[4:7], v[162:165], v[212:215], v[4:7]
	v_mfma_f32_16x16x32_bf16 v[0:3], v[170:173], v[212:215], v[0:3]
	s_setprio 0
	s_setprio 1
	v_mfma_f32_16x16x32_bf16 v[52:55], v[166:169], v[192:195], v[52:55]
	v_mfma_f32_16x16x32_bf16 v[48:51], v[174:177], v[192:195], v[48:51]
	v_mfma_f32_16x16x32_bf16 v[36:39], v[166:169], v[200:203], v[36:39]
	v_mfma_f32_16x16x32_bf16 v[32:35], v[174:177], v[200:203], v[32:35]
	v_mfma_f32_16x16x32_bf16 v[20:23], v[166:169], v[208:211], v[20:23]
	v_mfma_f32_16x16x32_bf16 v[16:19], v[174:177], v[208:211], v[16:19]
	v_mfma_f32_16x16x32_bf16 v[4:7], v[166:169], v[216:219], v[4:7]
	v_mfma_f32_16x16x32_bf16 v[0:3], v[174:177], v[216:219], v[0:3]
	s_barrier
	s_setprio 0
.Lpeel_mid_p4:
	s_add_i32 s57, 0, 0x18000
	s_add_i32 s58, 0, 0x1c000
	v_add_u32_e32 v140, s57, v184
	v_add_u32_e32 v174, s58, v184
	ds_read_b128 v[128:131], v140
	ds_read_b128 v[132:135], v140 offset:1024
	ds_read_b128 v[136:139], v140 offset:2048
	ds_read_b128 v[140:143], v140 offset:3072
	ds_read_b128 v[162:165], v174
	ds_read_b128 v[166:169], v174 offset:1024
	ds_read_b128 v[170:173], v174 offset:2048
	ds_read_b128 v[174:177], v174 offset:3072
	s_add_u32 s40, s40, 0x80000
	s_addc_u32 s41, s41, 0
	s_mov_b32 m0, s44
	v_lshl_add_u64 v[226:227], s[40:41], 0, v[150:151]
	ds_read_b128 v[178:181], v188 offset:32768
	ds_read_b128 v[192:195], v188 offset:33792
	ds_read_b128 v[196:199], v188 offset:34816
	ds_read_b128 v[200:203], v188 offset:35840
	ds_read_b128 v[204:207], v188 offset:36864
	ds_read_b128 v[208:211], v188 offset:37888
	ds_read_b128 v[212:215], v188 offset:38912
	ds_read_b128 v[216:219], v188 offset:39936
	global_load_lds_dwordx4 v[226:227], off
	v_lshl_add_u64 v[226:227], s[40:41], 0, v[146:147]
	s_mov_b32 m0, s45
	s_nop 0
	global_load_lds_dwordx4 v[226:227], off
	s_waitcnt vmcnt(8) lgkmcnt(0)
	s_setprio 1
	s_barrier
	v_mfma_f32_16x16x32_bf16 v[124:127], v[128:131], v[178:181], v[124:127]
	v_mfma_f32_16x16x32_bf16 v[120:123], v[136:139], v[178:181], v[120:123]
	v_mfma_f32_16x16x32_bf16 v[108:111], v[128:131], v[196:199], v[108:111]
	v_mfma_f32_16x16x32_bf16 v[104:107], v[136:139], v[196:199], v[104:107]
	v_mfma_f32_16x16x32_bf16 v[92:95], v[128:131], v[204:207], v[92:95]
	v_mfma_f32_16x16x32_bf16 v[88:91], v[136:139], v[204:207], v[88:91]
	v_mfma_f32_16x16x32_bf16 v[76:79], v[128:131], v[212:215], v[76:79]
	v_mfma_f32_16x16x32_bf16 v[72:75], v[136:139], v[212:215], v[72:75]
	s_setprio 0
	s_setprio 1
	v_mfma_f32_16x16x32_bf16 v[124:127], v[132:135], v[192:195], v[124:127]
	v_mfma_f32_16x16x32_bf16 v[120:123], v[140:143], v[192:195], v[120:123]
	v_mfma_f32_16x16x32_bf16 v[108:111], v[132:135], v[200:203], v[108:111]
	v_mfma_f32_16x16x32_bf16 v[104:107], v[140:143], v[200:203], v[104:107]
	v_mfma_f32_16x16x32_bf16 v[92:95], v[132:135], v[208:211], v[92:95]
	v_mfma_f32_16x16x32_bf16 v[88:91], v[140:143], v[208:211], v[88:91]
	v_mfma_f32_16x16x32_bf16 v[76:79], v[132:135], v[216:219], v[76:79]
	v_mfma_f32_16x16x32_bf16 v[72:75], v[140:143], v[216:219], v[72:75]
	s_setprio 0
	s_setprio 1
	v_mfma_f32_16x16x32_bf16 v[116:119], v[162:165], v[178:181], v[116:119]
	v_mfma_f32_16x16x32_bf16 v[112:115], v[170:173], v[178:181], v[112:115]
	v_mfma_f32_16x16x32_bf16 v[100:103], v[162:165], v[196:199], v[100:103]
	v_mfma_f32_16x16x32_bf16 v[96:99], v[170:173], v[196:199], v[96:99]
	v_mfma_f32_16x16x32_bf16 v[84:87], v[162:165], v[204:207], v[84:87]
	v_mfma_f32_16x16x32_bf16 v[80:83], v[170:173], v[204:207], v[80:83]
	v_mfma_f32_16x16x32_bf16 v[68:71], v[162:165], v[212:215], v[68:71]
	v_mfma_f32_16x16x32_bf16 v[64:67], v[170:173], v[212:215], v[64:67]
	s_setprio 0
	s_setprio 1
	v_mfma_f32_16x16x32_bf16 v[116:119], v[166:169], v[192:195], v[116:119]
	v_mfma_f32_16x16x32_bf16 v[112:115], v[174:177], v[192:195], v[112:115]
	v_mfma_f32_16x16x32_bf16 v[100:103], v[166:169], v[200:203], v[100:103]
	v_mfma_f32_16x16x32_bf16 v[96:99], v[174:177], v[200:203], v[96:99]
	v_mfma_f32_16x16x32_bf16 v[84:87], v[166:169], v[208:211], v[84:87]
	v_mfma_f32_16x16x32_bf16 v[80:83], v[174:177], v[208:211], v[80:83]
	v_mfma_f32_16x16x32_bf16 v[68:71], v[166:169], v[216:219], v[68:71]
	v_mfma_f32_16x16x32_bf16 v[64:67], v[174:177], v[216:219], v[64:67]
	s_barrier
	s_setprio 0
	s_add_i32 s40, s57, s35
	v_lshl_add_u64 v[182:183], v[182:183], 0, s[14:15]
	s_mov_b32 m0, s40
	ds_read_b128 v[178:181], v188 offset:49152
	ds_read_b128 v[192:195], v188 offset:50176
	ds_read_b128 v[196:199], v188 offset:51200
	ds_read_b128 v[200:203], v188 offset:52224
	ds_read_b128 v[204:207], v188 offset:53248
	ds_read_b128 v[208:211], v188 offset:54272
	ds_read_b128 v[212:215], v188 offset:55296
	ds_read_b128 v[216:219], v188 offset:56320
	global_load_lds_dwordx4 v[182:183], off
	s_add_i32 m0, s40, 0x2000
	s_add_u32 s38, s38, 0x80080
	v_lshl_add_u64 v[182:183], v[220:221], 0, s[14:15]
	s_addc_u32 s39, s39, 0
	s_add_i32 s40, s58, s35
	global_load_lds_dwordx4 v[182:183], off
	v_lshl_add_u64 v[182:183], s[38:39], 0, v[148:149]
	s_mov_b32 m0, s40
	s_nop 0
	global_load_lds_dwordx4 v[182:183], off
	v_lshl_add_u64 v[182:183], s[38:39], 0, v[144:145]
	s_add_i32 m0, s40, 0x2000
	s_nop 0
	global_load_lds_dwordx4 v[182:183], off
	v_lshl_add_u64 v[182:183], v[222:223], 0, s[14:15]
	s_mov_b32 m0, s49
	s_nop 0
	global_load_lds_dwordx4 v[182:183], off
	v_lshl_add_u64 v[182:183], v[224:225], 0, s[14:15]
	s_mov_b32 m0, s50
	s_nop 0
	global_load_lds_dwordx4 v[182:183], off
	s_waitcnt vmcnt(8) lgkmcnt(0)
	s_setprio 1
	s_barrier
	v_mfma_f32_16x16x32_bf16 v[60:63], v[128:131], v[178:181], v[60:63]
	v_mfma_f32_16x16x32_bf16 v[56:59], v[136:139], v[178:181], v[56:59]
	v_mfma_f32_16x16x32_bf16 v[44:47], v[128:131], v[196:199], v[44:47]
	v_mfma_f32_16x16x32_bf16 v[40:43], v[136:139], v[196:199], v[40:43]
	v_mfma_f32_16x16x32_bf16 v[28:31], v[128:131], v[204:207], v[28:31]
	v_mfma_f32_16x16x32_bf16 v[24:27], v[136:139], v[204:207], v[24:27]
	v_mfma_f32_16x16x32_bf16 v[12:15], v[128:131], v[212:215], v[12:15]
	v_mfma_f32_16x16x32_bf16 v[8:11], v[136:139], v[212:215], v[8:11]
	s_setprio 0
	s_setprio 1
	v_mfma_f32_16x16x32_bf16 v[60:63], v[132:135], v[192:195], v[60:63]
	v_mfma_f32_16x16x32_bf16 v[56:59], v[140:143], v[192:195], v[56:59]
	v_mfma_f32_16x16x32_bf16 v[44:47], v[132:135], v[200:203], v[44:47]
	v_mfma_f32_16x16x32_bf16 v[40:43], v[140:143], v[200:203], v[40:43]
	v_mfma_f32_16x16x32_bf16 v[28:31], v[132:135], v[208:211], v[28:31]
	v_mfma_f32_16x16x32_bf16 v[24:27], v[140:143], v[208:211], v[24:27]
	v_mfma_f32_16x16x32_bf16 v[12:15], v[132:135], v[216:219], v[12:15]
	v_mfma_f32_16x16x32_bf16 v[8:11], v[140:143], v[216:219], v[8:11]
	s_setprio 0
	s_setprio 1
	v_mfma_f32_16x16x32_bf16 v[52:55], v[162:165], v[178:181], v[52:55]
	v_mfma_f32_16x16x32_bf16 v[48:51], v[170:173], v[178:181], v[48:51]
	v_mfma_f32_16x16x32_bf16 v[36:39], v[162:165], v[196:199], v[36:39]
	v_mfma_f32_16x16x32_bf16 v[32:35], v[170:173], v[196:199], v[32:35]
	s_add_i32 s56, s56, 2
	v_mfma_f32_16x16x32_bf16 v[20:23], v[162:165], v[204:207], v[20:23]
	s_add_u32 s6, s6, 0x100
	v_mfma_f32_16x16x32_bf16 v[16:19], v[170:173], v[204:207], v[16:19]
	s_addc_u32 s7, s7, 0
	v_mfma_f32_16x16x32_bf16 v[4:7], v[162:165], v[212:215], v[4:7]
	s_add_u32 s5, s5, 0x100
	v_mfma_f32_16x16x32_bf16 v[0:3], v[170:173], v[212:215], v[0:3]
	s_setprio 0
	s_setprio 1
	s_addc_u32 s25, s25, 0
	v_mfma_f32_16x16x32_bf16 v[52:55], v[166:169], v[192:195], v[52:55]
	s_cmp_gt_u32 s56, 29
	v_mfma_f32_16x16x32_bf16 v[48:51], v[174:177], v[192:195], v[48:51]
	v_mfma_f32_16x16x32_bf16 v[36:39], v[166:169], v[200:203], v[36:39]
	v_mfma_f32_16x16x32_bf16 v[32:35], v[174:177], v[200:203], v[32:35]
	v_mfma_f32_16x16x32_bf16 v[20:23], v[166:169], v[208:211], v[20:23]
	v_mfma_f32_16x16x32_bf16 v[16:19], v[174:177], v[208:211], v[16:19]
	v_mfma_f32_16x16x32_bf16 v[4:7], v[166:169], v[216:219], v[4:7]
	v_mfma_f32_16x16x32_bf16 v[0:3], v[174:177], v[216:219], v[0:3]
	s_barrier
	s_setprio 0
	s_cbranch_scc0 .LBB0_672
	s_and_b64 vcc, exec, s[18:19]
	s_cbranch_vccz .LBB0_675
	s_barrier
